# HGRN: V image triple-buffered in LDS (16 KiB static LDS), V and z/q fetched one chunk ahead, DMA issue interleaved with scan
# speedup vs baseline: 1.0089x; 1.0089x over previous
.Lh2_prep:
	v_and_b32_e32 v244, 63, v200
	v_lshrrev_b32_e32 v245, 2, v244
	v_lshrrev_b32_e32 v243, 4, v244
	s_lshl_b32 s1, s8, 12
	s_add_u32 s13, s1, 0xfff
	s_cmp_eq_u32 s12, 0
	s_cselect_b64 s[18:19], -1, 0
	v_mov_b32_e32 v242, 0x1c00
	v_and_b32_e32 v241, 3, v244
	v_and_b32_e32 v240, 3, v243
	v_xor_b32_e32 v241, v241, v240
	v_lshlrev_b32_e32 v241, 4, v241
	v_add_u32_e32 v240, 0, v245
	v_add_u32_e32 v239, s1, v240
	v_sub_u32_e32 v240, s13, v240
	v_cndmask_b32_e64 v239, v240, v239, s[18:19]
	v_mul_lo_u32 v239, v239, v242
	v_add_u32_e32 v228, v239, v241
	v_add_u32_e32 v240, 16, v245
	v_add_u32_e32 v239, s1, v240
	v_sub_u32_e32 v240, s13, v240
	v_cndmask_b32_e64 v239, v240, v239, s[18:19]
	v_mul_lo_u32 v239, v239, v242
	v_add_u32_e32 v230, v239, v241
	v_add_u32_e32 v240, 32, v245
	v_add_u32_e32 v239, s1, v240
	v_sub_u32_e32 v240, s13, v240
	v_cndmask_b32_e64 v239, v240, v239, s[18:19]
	v_mul_lo_u32 v239, v239, v242
	v_add_u32_e32 v231, v239, v241
	v_add_u32_e32 v240, 48, v245
	v_add_u32_e32 v239, s1, v240
	v_sub_u32_e32 v240, s13, v240
	v_cndmask_b32_e64 v239, v240, v239, s[18:19]
	v_mul_lo_u32 v239, v239, v242
	v_add_u32_e32 v232, v239, v241
	s_lshl_b32 s17, s0, 4
	v_add_u32_e32 v240, 0, v243
	v_add_u32_e32 v240, s17, v240
	v_add_u32_e32 v239, s1, v240
	v_sub_u32_e32 v240, s13, v240
	v_cndmask_b32_e64 v239, v240, v239, s[18:19]
	v_mul_lo_u32 v239, v239, v242
	v_lshl_or_b32 v240, v243, 2, 0
	v_and_b32_e32 v238, 15, v244
	v_xor_b32_e32 v240, v240, v238
	v_lshl_add_u32 v252, v240, 4, v239
	v_add_u32_e32 v240, 4, v243
	v_add_u32_e32 v240, s17, v240
	v_add_u32_e32 v239, s1, v240
	v_sub_u32_e32 v240, s13, v240
	v_cndmask_b32_e64 v239, v240, v239, s[18:19]
	v_mul_lo_u32 v239, v239, v242
	v_lshl_or_b32 v240, v243, 2, 1
	v_and_b32_e32 v238, 15, v244
	v_xor_b32_e32 v240, v240, v238
	v_lshl_add_u32 v253, v240, 4, v239
	v_add_u32_e32 v240, 8, v243
	v_add_u32_e32 v240, s17, v240
	v_add_u32_e32 v239, s1, v240
	v_sub_u32_e32 v240, s13, v240
	v_cndmask_b32_e64 v239, v240, v239, s[18:19]
	v_mul_lo_u32 v239, v239, v242
	v_lshl_or_b32 v240, v243, 2, 2
	v_and_b32_e32 v238, 15, v244
	v_xor_b32_e32 v240, v240, v238
	v_lshl_add_u32 v254, v240, 4, v239
	v_add_u32_e32 v240, 12, v243
	v_add_u32_e32 v240, s17, v240
	v_add_u32_e32 v239, s1, v240
	v_sub_u32_e32 v240, s13, v240
	v_cndmask_b32_e64 v239, v240, v239, s[18:19]
	v_mul_lo_u32 v239, v239, v242
	v_lshl_or_b32 v240, v243, 2, 3
	v_and_b32_e32 v238, 15, v244
	v_xor_b32_e32 v240, v240, v238
	v_lshl_add_u32 v255, v240, 4, v239
	s_mov_b32 s33, 0x70000
	s_sub_u32 s13, 0, s33
	s_cmp_eq_u32 s12, 0
	s_cselect_b32 s33, s33, s13
	s_lshl_b32 s13, s9, 8
	s_add_u32 s34, s92, s13
	s_addc_u32 s35, s93, 0
	s_lshl_b32 s1, s0, 6
	s_add_u32 s30, s34, s1
	s_addc_u32 s31, s35, 0
	s_add_u32 s34, s34, 0xc00
	s_addc_u32 s35, s35, 0
	s_movk_i32 s1, 0x800
	s_cmp_eq_u32 s12, 0
	s_cselect_b32 s1, 0x400, s1
	s_add_u32 s14, s30, s1
	s_addc_u32 s15, s31, 0
	v_and_b32_e32 v241, 3, v244
	v_xor_b32_e32 v241, s0, v241
	v_lshlrev_b32_e32 v241, 6, v241
	v_lshl_add_u32 v241, v244, 8, v241
	v_bfe_u32 v240, v244, 2, 2
	v_xor_b32_e32 v239, 0, v240
	v_lshl_add_u32 v222, v239, 4, v241
	v_xor_b32_e32 v239, 1, v240
	v_lshl_add_u32 v223, v239, 4, v241
	v_xor_b32_e32 v239, 2, v240
	v_lshl_add_u32 v224, v239, 4, v241
	v_xor_b32_e32 v239, 3, v240
	v_lshl_add_u32 v225, v239, 4, v241
	v_mov_b32_e32 v239, 0x110
	v_mul_lo_u32 v241, v244, v239
	s_lshl_b32 s1, s0, 6
	v_add_u32_e32 v241, s1, v241
	v_add_u32_e32 v226, 0x10400, v241
	v_add_u32_e32 v227, 0x14800, v241
	s_lshl_b32 s1, s0, 7
	v_mov_b32_e32 v247, s1
	s_lshl_b32 s71, s0, 13
	s_add_u32 s71, s71, 0x1b400
	s_lshl_b32 s72, s0, 12
	v_lshlrev_b32_e32 v241, 6, v244
	v_add_u32_e32 v241, s71, v241
	v_xor_b32_e32 v239, 0, v240
	v_lshl_add_u32 v248, v239, 4, v241
	v_xor_b32_e32 v239, 1, v240
	v_lshl_add_u32 v249, v239, 4, v241
	v_xor_b32_e32 v239, 2, v240
	v_lshl_add_u32 v250, v239, 4, v241
	v_xor_b32_e32 v239, 3, v240
	v_lshl_add_u32 v251, v239, 4, v241
	s_add_u32 s1, s72, 0x8400
	s_add_u32 m0, s1, 0
	s_nop 0
	global_load_lds_dwordx4 v252, s[34:35]
	s_add_u32 m0, s1, 1024
	s_nop 0
	global_load_lds_dwordx4 v253, s[34:35]
	s_add_u32 m0, s1, 2048
	s_nop 0
	global_load_lds_dwordx4 v254, s[34:35]
	s_add_u32 m0, s1, 3072
	s_nop 0
	global_load_lds_dwordx4 v255, s[34:35]
	v_add_u32_e32 v252, s33, v252
	v_add_u32_e32 v253, s33, v253
	v_add_u32_e32 v254, s33, v254
	v_add_u32_e32 v255, s33, v255
	s_mov_b32 s77, 0xc400
	s_add_u32 m0, s71, 0
	s_nop 0
	global_load_lds_dwordx4 v228, s[14:15]
	s_add_u32 m0, s71, 4096
	s_nop 0
	global_load_lds_dwordx4 v228, s[30:31]
	s_add_u32 m0, s71, 1024
	s_nop 0
	global_load_lds_dwordx4 v230, s[14:15]
	s_add_u32 m0, s71, 5120
	s_nop 0
	global_load_lds_dwordx4 v230, s[30:31]
	s_add_u32 m0, s71, 2048
	s_nop 0
	global_load_lds_dwordx4 v231, s[14:15]
	s_add_u32 m0, s71, 6144
	s_nop 0
	global_load_lds_dwordx4 v231, s[30:31]
	s_add_u32 m0, s71, 3072
	s_nop 0
	global_load_lds_dwordx4 v232, s[14:15]
	s_add_u32 m0, s71, 7168
	s_nop 0
	global_load_lds_dwordx4 v232, s[30:31]
	v_add_u32_e32 v228, s33, v228
	v_add_u32_e32 v230, s33, v230
	v_add_u32_e32 v231, s33, v231
	v_add_u32_e32 v232, s33, v232
	s_mov_b32 s70, 0
.Lh2_prep_loop:
	s_waitcnt vmcnt(0)
	ds_read_b128 v[234:237], v248
	ds_read_b128 v[238:241], v249
	ds_read_b128 v[242:245], v250
	ds_read_b128 v[168:171], v251
	ds_read_b128 v[0:3], v248 offset:4096
	ds_read_b128 v[4:7], v249 offset:4096
	ds_read_b128 v[8:11], v250 offset:4096
	ds_read_b128 v[12:15], v251 offset:4096
	s_cmp_eq_u32 s70, 31
	s_cselect_b32 s76, 0, s33
	s_add_u32 s1, s72, s77
	s_add_u32 s77, s77, 0x4000
	s_cmp_eq_u32 s77, 0x10400
	s_cselect_b32 s77, 0x24000, s77
	s_cmp_eq_u32 s77, 0x28000
	s_cselect_b32 s77, 0x8400, s77
	s_waitcnt lgkmcnt(4)
	s_add_u32 m0, s1, 0
	s_nop 0
	global_load_lds_dwordx4 v252, s[34:35]
	v_lshlrev_b32_e32 v96, 16, v234
	v_and_b32_e32 v97, 0xffff0000, v234
	v_lshlrev_b32_e32 v98, 16, v235
	v_and_b32_e32 v99, 0xffff0000, v235
	v_lshlrev_b32_e32 v100, 16, v236
	v_and_b32_e32 v101, 0xffff0000, v236
	v_lshlrev_b32_e32 v102, 16, v237
	v_and_b32_e32 v103, 0xffff0000, v237
	v_lshlrev_b32_e32 v104, 16, v238
	v_and_b32_e32 v105, 0xffff0000, v238
	v_lshlrev_b32_e32 v106, 16, v239
	v_and_b32_e32 v107, 0xffff0000, v239
	v_lshlrev_b32_e32 v108, 16, v240
	v_and_b32_e32 v109, 0xffff0000, v240
	v_lshlrev_b32_e32 v110, 16, v241
	v_and_b32_e32 v111, 0xffff0000, v241
	v_lshlrev_b32_e32 v112, 16, v242
	v_and_b32_e32 v113, 0xffff0000, v242
	v_lshlrev_b32_e32 v114, 16, v243
	v_and_b32_e32 v115, 0xffff0000, v243
	v_lshlrev_b32_e32 v116, 16, v244
	s_add_u32 m0, s1, 1024
	s_nop 0
	global_load_lds_dwordx4 v253, s[34:35]
	v_and_b32_e32 v117, 0xffff0000, v244
	v_lshlrev_b32_e32 v118, 16, v245
	v_and_b32_e32 v119, 0xffff0000, v245
	v_lshlrev_b32_e32 v120, 16, v168
	v_and_b32_e32 v121, 0xffff0000, v168
	v_lshlrev_b32_e32 v122, 16, v169
	v_and_b32_e32 v123, 0xffff0000, v169
	v_lshlrev_b32_e32 v124, 16, v170
	v_and_b32_e32 v125, 0xffff0000, v170
	v_lshlrev_b32_e32 v126, 16, v171
	v_and_b32_e32 v127, 0xffff0000, v171
	s_waitcnt lgkmcnt(0)
	v_sub_f32_e32 v128, 1.0, v96
	v_sub_f32_e32 v129, 1.0, v97
	v_sub_f32_e32 v130, 1.0, v98
	v_sub_f32_e32 v131, 1.0, v99
	v_sub_f32_e32 v132, 1.0, v100
	v_sub_f32_e32 v133, 1.0, v101
	v_sub_f32_e32 v134, 1.0, v102
	v_sub_f32_e32 v135, 1.0, v103
	v_sub_f32_e32 v136, 1.0, v104
	v_sub_f32_e32 v137, 1.0, v105
	s_add_u32 m0, s1, 2048
	s_nop 0
	global_load_lds_dwordx4 v254, s[34:35]
	v_sub_f32_e32 v138, 1.0, v106
	v_sub_f32_e32 v139, 1.0, v107
	v_sub_f32_e32 v140, 1.0, v108
	v_sub_f32_e32 v141, 1.0, v109
	v_sub_f32_e32 v142, 1.0, v110
	v_sub_f32_e32 v143, 1.0, v111
	v_sub_f32_e32 v144, 1.0, v112
	v_sub_f32_e32 v145, 1.0, v113
	v_sub_f32_e32 v146, 1.0, v114
	v_sub_f32_e32 v147, 1.0, v115
	v_sub_f32_e32 v148, 1.0, v116
	v_sub_f32_e32 v149, 1.0, v117
	v_sub_f32_e32 v150, 1.0, v118
	v_sub_f32_e32 v151, 1.0, v119
	v_sub_f32_e32 v152, 1.0, v120
	v_sub_f32_e32 v153, 1.0, v121
	v_sub_f32_e32 v154, 1.0, v122
	v_sub_f32_e32 v155, 1.0, v123
	v_sub_f32_e32 v156, 1.0, v124
	v_sub_f32_e32 v157, 1.0, v125
	v_sub_f32_e32 v158, 1.0, v126
	s_add_u32 m0, s1, 3072
	s_nop 0
	global_load_lds_dwordx4 v255, s[34:35]
	v_add_u32_e32 v252, s76, v252
	v_add_u32_e32 v253, s76, v253
	v_add_u32_e32 v254, s76, v254
	v_add_u32_e32 v255, s76, v255
	v_sub_f32_e32 v159, 1.0, v127
	v_mul_f32_dpp v128, v128, v128 row_shr:1 row_mask:0xf bank_mask:0xf
	v_mul_f32_dpp v129, v129, v129 row_shr:1 row_mask:0xf bank_mask:0xf
	v_mul_f32_dpp v130, v130, v130 row_shr:1 row_mask:0xf bank_mask:0xf
	v_mul_f32_dpp v131, v131, v131 row_shr:1 row_mask:0xf bank_mask:0xf
	v_mul_f32_dpp v132, v132, v132 row_shr:1 row_mask:0xf bank_mask:0xf
	v_mul_f32_dpp v133, v133, v133 row_shr:1 row_mask:0xf bank_mask:0xf
	v_mul_f32_dpp v134, v134, v134 row_shr:1 row_mask:0xf bank_mask:0xf
	v_mul_f32_dpp v135, v135, v135 row_shr:1 row_mask:0xf bank_mask:0xf
	v_mul_f32_dpp v136, v136, v136 row_shr:1 row_mask:0xf bank_mask:0xf
	v_mul_f32_dpp v137, v137, v137 row_shr:1 row_mask:0xf bank_mask:0xf
	v_mul_f32_dpp v138, v138, v138 row_shr:1 row_mask:0xf bank_mask:0xf
	v_mul_f32_dpp v139, v139, v139 row_shr:1 row_mask:0xf bank_mask:0xf
	v_mul_f32_dpp v140, v140, v140 row_shr:1 row_mask:0xf bank_mask:0xf
	v_mul_f32_dpp v141, v141, v141 row_shr:1 row_mask:0xf bank_mask:0xf
	v_mul_f32_dpp v142, v142, v142 row_shr:1 row_mask:0xf bank_mask:0xf
	v_mul_f32_dpp v143, v143, v143 row_shr:1 row_mask:0xf bank_mask:0xf
	v_mul_f32_dpp v144, v144, v144 row_shr:1 row_mask:0xf bank_mask:0xf
	v_mul_f32_dpp v145, v145, v145 row_shr:1 row_mask:0xf bank_mask:0xf
	v_mul_f32_dpp v146, v146, v146 row_shr:1 row_mask:0xf bank_mask:0xf
	v_mul_f32_dpp v147, v147, v147 row_shr:1 row_mask:0xf bank_mask:0xf
	s_add_u32 m0, s71, 0
	s_nop 0
	global_load_lds_dwordx4 v228, s[14:15]
	v_mul_f32_dpp v148, v148, v148 row_shr:1 row_mask:0xf bank_mask:0xf
	v_mul_f32_dpp v149, v149, v149 row_shr:1 row_mask:0xf bank_mask:0xf
	v_mul_f32_dpp v150, v150, v150 row_shr:1 row_mask:0xf bank_mask:0xf
	v_mul_f32_dpp v151, v151, v151 row_shr:1 row_mask:0xf bank_mask:0xf
	v_mul_f32_dpp v152, v152, v152 row_shr:1 row_mask:0xf bank_mask:0xf
	v_mul_f32_dpp v153, v153, v153 row_shr:1 row_mask:0xf bank_mask:0xf
	v_mul_f32_dpp v154, v154, v154 row_shr:1 row_mask:0xf bank_mask:0xf
	v_mul_f32_dpp v155, v155, v155 row_shr:1 row_mask:0xf bank_mask:0xf
	v_mul_f32_dpp v156, v156, v156 row_shr:1 row_mask:0xf bank_mask:0xf
	v_mul_f32_dpp v157, v157, v157 row_shr:1 row_mask:0xf bank_mask:0xf
	v_mul_f32_dpp v158, v158, v158 row_shr:1 row_mask:0xf bank_mask:0xf
	v_mul_f32_dpp v159, v159, v159 row_shr:1 row_mask:0xf bank_mask:0xf
	v_mul_f32_dpp v128, v128, v128 row_shr:2 row_mask:0xf bank_mask:0xf
	v_mul_f32_dpp v129, v129, v129 row_shr:2 row_mask:0xf bank_mask:0xf
	v_mul_f32_dpp v130, v130, v130 row_shr:2 row_mask:0xf bank_mask:0xf
	v_mul_f32_dpp v131, v131, v131 row_shr:2 row_mask:0xf bank_mask:0xf
	v_mul_f32_dpp v132, v132, v132 row_shr:2 row_mask:0xf bank_mask:0xf
	v_mul_f32_dpp v133, v133, v133 row_shr:2 row_mask:0xf bank_mask:0xf
	v_mul_f32_dpp v134, v134, v134 row_shr:2 row_mask:0xf bank_mask:0xf
	v_mul_f32_dpp v135, v135, v135 row_shr:2 row_mask:0xf bank_mask:0xf
	v_mul_f32_dpp v136, v136, v136 row_shr:2 row_mask:0xf bank_mask:0xf
	s_add_u32 m0, s71, 4096
	s_nop 0
	global_load_lds_dwordx4 v228, s[30:31]
	v_mul_f32_dpp v137, v137, v137 row_shr:2 row_mask:0xf bank_mask:0xf
	v_mul_f32_dpp v138, v138, v138 row_shr:2 row_mask:0xf bank_mask:0xf
	v_mul_f32_dpp v139, v139, v139 row_shr:2 row_mask:0xf bank_mask:0xf
	v_mul_f32_dpp v140, v140, v140 row_shr:2 row_mask:0xf bank_mask:0xf
	v_mul_f32_dpp v141, v141, v141 row_shr:2 row_mask:0xf bank_mask:0xf
	v_mul_f32_dpp v142, v142, v142 row_shr:2 row_mask:0xf bank_mask:0xf
	v_mul_f32_dpp v143, v143, v143 row_shr:2 row_mask:0xf bank_mask:0xf
	v_mul_f32_dpp v144, v144, v144 row_shr:2 row_mask:0xf bank_mask:0xf
	v_mul_f32_dpp v145, v145, v145 row_shr:2 row_mask:0xf bank_mask:0xf
	v_mul_f32_dpp v146, v146, v146 row_shr:2 row_mask:0xf bank_mask:0xf
	v_mul_f32_dpp v147, v147, v147 row_shr:2 row_mask:0xf bank_mask:0xf
	v_mul_f32_dpp v148, v148, v148 row_shr:2 row_mask:0xf bank_mask:0xf
	v_mul_f32_dpp v149, v149, v149 row_shr:2 row_mask:0xf bank_mask:0xf
	v_mul_f32_dpp v150, v150, v150 row_shr:2 row_mask:0xf bank_mask:0xf
	v_mul_f32_dpp v151, v151, v151 row_shr:2 row_mask:0xf bank_mask:0xf
	v_mul_f32_dpp v152, v152, v152 row_shr:2 row_mask:0xf bank_mask:0xf
	v_mul_f32_dpp v153, v153, v153 row_shr:2 row_mask:0xf bank_mask:0xf
	v_mul_f32_dpp v154, v154, v154 row_shr:2 row_mask:0xf bank_mask:0xf
	v_mul_f32_dpp v155, v155, v155 row_shr:2 row_mask:0xf bank_mask:0xf
	v_mul_f32_dpp v156, v156, v156 row_shr:2 row_mask:0xf bank_mask:0xf
	v_mul_f32_dpp v157, v157, v157 row_shr:2 row_mask:0xf bank_mask:0xf
	s_add_u32 m0, s71, 1024
	s_nop 0
	global_load_lds_dwordx4 v230, s[14:15]
	v_mul_f32_dpp v158, v158, v158 row_shr:2 row_mask:0xf bank_mask:0xf
	v_mul_f32_dpp v159, v159, v159 row_shr:2 row_mask:0xf bank_mask:0xf
	v_mul_f32_dpp v128, v128, v128 row_shr:4 row_mask:0xf bank_mask:0xf
	v_mul_f32_dpp v129, v129, v129 row_shr:4 row_mask:0xf bank_mask:0xf
	v_mul_f32_dpp v130, v130, v130 row_shr:4 row_mask:0xf bank_mask:0xf
	v_mul_f32_dpp v131, v131, v131 row_shr:4 row_mask:0xf bank_mask:0xf
	v_mul_f32_dpp v132, v132, v132 row_shr:4 row_mask:0xf bank_mask:0xf
	v_mul_f32_dpp v133, v133, v133 row_shr:4 row_mask:0xf bank_mask:0xf
	v_mul_f32_dpp v134, v134, v134 row_shr:4 row_mask:0xf bank_mask:0xf
	v_mul_f32_dpp v135, v135, v135 row_shr:4 row_mask:0xf bank_mask:0xf
	v_mul_f32_dpp v136, v136, v136 row_shr:4 row_mask:0xf bank_mask:0xf
	v_mul_f32_dpp v137, v137, v137 row_shr:4 row_mask:0xf bank_mask:0xf
	v_mul_f32_dpp v138, v138, v138 row_shr:4 row_mask:0xf bank_mask:0xf
	v_mul_f32_dpp v139, v139, v139 row_shr:4 row_mask:0xf bank_mask:0xf
	v_mul_f32_dpp v140, v140, v140 row_shr:4 row_mask:0xf bank_mask:0xf
	v_mul_f32_dpp v141, v141, v141 row_shr:4 row_mask:0xf bank_mask:0xf
	v_mul_f32_dpp v142, v142, v142 row_shr:4 row_mask:0xf bank_mask:0xf
	v_mul_f32_dpp v143, v143, v143 row_shr:4 row_mask:0xf bank_mask:0xf
	v_mul_f32_dpp v144, v144, v144 row_shr:4 row_mask:0xf bank_mask:0xf
	v_mul_f32_dpp v145, v145, v145 row_shr:4 row_mask:0xf bank_mask:0xf
	v_mul_f32_dpp v146, v146, v146 row_shr:4 row_mask:0xf bank_mask:0xf
	s_add_u32 m0, s71, 5120
	s_nop 0
	global_load_lds_dwordx4 v230, s[30:31]
	v_mul_f32_dpp v147, v147, v147 row_shr:4 row_mask:0xf bank_mask:0xf
	v_mul_f32_dpp v148, v148, v148 row_shr:4 row_mask:0xf bank_mask:0xf
	v_mul_f32_dpp v149, v149, v149 row_shr:4 row_mask:0xf bank_mask:0xf
	v_mul_f32_dpp v150, v150, v150 row_shr:4 row_mask:0xf bank_mask:0xf
	v_mul_f32_dpp v151, v151, v151 row_shr:4 row_mask:0xf bank_mask:0xf
	v_mul_f32_dpp v152, v152, v152 row_shr:4 row_mask:0xf bank_mask:0xf
	v_mul_f32_dpp v153, v153, v153 row_shr:4 row_mask:0xf bank_mask:0xf
	v_mul_f32_dpp v154, v154, v154 row_shr:4 row_mask:0xf bank_mask:0xf
	v_mul_f32_dpp v155, v155, v155 row_shr:4 row_mask:0xf bank_mask:0xf
	v_mul_f32_dpp v156, v156, v156 row_shr:4 row_mask:0xf bank_mask:0xf
	v_mul_f32_dpp v157, v157, v157 row_shr:4 row_mask:0xf bank_mask:0xf
	v_mul_f32_dpp v158, v158, v158 row_shr:4 row_mask:0xf bank_mask:0xf
	v_mul_f32_dpp v159, v159, v159 row_shr:4 row_mask:0xf bank_mask:0xf
	v_mul_f32_dpp v128, v128, v128 row_shr:8 row_mask:0xf bank_mask:0xf
	v_mul_f32_dpp v129, v129, v129 row_shr:8 row_mask:0xf bank_mask:0xf
	v_mul_f32_dpp v130, v130, v130 row_shr:8 row_mask:0xf bank_mask:0xf
	v_mul_f32_dpp v131, v131, v131 row_shr:8 row_mask:0xf bank_mask:0xf
	v_mul_f32_dpp v132, v132, v132 row_shr:8 row_mask:0xf bank_mask:0xf
	v_mul_f32_dpp v133, v133, v133 row_shr:8 row_mask:0xf bank_mask:0xf
	v_mul_f32_dpp v134, v134, v134 row_shr:8 row_mask:0xf bank_mask:0xf
	v_mul_f32_dpp v135, v135, v135 row_shr:8 row_mask:0xf bank_mask:0xf
	s_add_u32 m0, s71, 2048
	s_nop 0
	global_load_lds_dwordx4 v231, s[14:15]
	v_mul_f32_dpp v136, v136, v136 row_shr:8 row_mask:0xf bank_mask:0xf
	v_mul_f32_dpp v137, v137, v137 row_shr:8 row_mask:0xf bank_mask:0xf
	v_mul_f32_dpp v138, v138, v138 row_shr:8 row_mask:0xf bank_mask:0xf
	v_mul_f32_dpp v139, v139, v139 row_shr:8 row_mask:0xf bank_mask:0xf
	v_mul_f32_dpp v140, v140, v140 row_shr:8 row_mask:0xf bank_mask:0xf
	v_mul_f32_dpp v141, v141, v141 row_shr:8 row_mask:0xf bank_mask:0xf
	v_mul_f32_dpp v142, v142, v142 row_shr:8 row_mask:0xf bank_mask:0xf
	v_mul_f32_dpp v143, v143, v143 row_shr:8 row_mask:0xf bank_mask:0xf
	v_mul_f32_dpp v144, v144, v144 row_shr:8 row_mask:0xf bank_mask:0xf
	v_mul_f32_dpp v145, v145, v145 row_shr:8 row_mask:0xf bank_mask:0xf
	v_mul_f32_dpp v146, v146, v146 row_shr:8 row_mask:0xf bank_mask:0xf
	v_mul_f32_dpp v147, v147, v147 row_shr:8 row_mask:0xf bank_mask:0xf
	v_mul_f32_dpp v148, v148, v148 row_shr:8 row_mask:0xf bank_mask:0xf
	v_mul_f32_dpp v149, v149, v149 row_shr:8 row_mask:0xf bank_mask:0xf
	v_mul_f32_dpp v150, v150, v150 row_shr:8 row_mask:0xf bank_mask:0xf
	v_mul_f32_dpp v151, v151, v151 row_shr:8 row_mask:0xf bank_mask:0xf
	v_mul_f32_dpp v152, v152, v152 row_shr:8 row_mask:0xf bank_mask:0xf
	v_mul_f32_dpp v153, v153, v153 row_shr:8 row_mask:0xf bank_mask:0xf
	v_mul_f32_dpp v154, v154, v154 row_shr:8 row_mask:0xf bank_mask:0xf
	v_mul_f32_dpp v155, v155, v155 row_shr:8 row_mask:0xf bank_mask:0xf
	v_mul_f32_dpp v156, v156, v156 row_shr:8 row_mask:0xf bank_mask:0xf
	s_add_u32 m0, s71, 6144
	s_nop 0
	global_load_lds_dwordx4 v231, s[30:31]
	v_mul_f32_dpp v157, v157, v157 row_shr:8 row_mask:0xf bank_mask:0xf
	v_mul_f32_dpp v158, v158, v158 row_shr:8 row_mask:0xf bank_mask:0xf
	v_mul_f32_dpp v159, v159, v159 row_shr:8 row_mask:0xf bank_mask:0xf
	v_mul_f32_dpp v128, v128, v128 row_bcast:15 row_mask:0xa bank_mask:0xf
	v_mul_f32_dpp v129, v129, v129 row_bcast:15 row_mask:0xa bank_mask:0xf
	v_mul_f32_dpp v130, v130, v130 row_bcast:15 row_mask:0xa bank_mask:0xf
	v_mul_f32_dpp v131, v131, v131 row_bcast:15 row_mask:0xa bank_mask:0xf
	v_mul_f32_dpp v132, v132, v132 row_bcast:15 row_mask:0xa bank_mask:0xf
	v_mul_f32_dpp v133, v133, v133 row_bcast:15 row_mask:0xa bank_mask:0xf
	v_mul_f32_dpp v134, v134, v134 row_bcast:15 row_mask:0xa bank_mask:0xf
	v_mul_f32_dpp v135, v135, v135 row_bcast:15 row_mask:0xa bank_mask:0xf
	v_mul_f32_dpp v136, v136, v136 row_bcast:15 row_mask:0xa bank_mask:0xf
	v_mul_f32_dpp v137, v137, v137 row_bcast:15 row_mask:0xa bank_mask:0xf
	v_mul_f32_dpp v138, v138, v138 row_bcast:15 row_mask:0xa bank_mask:0xf
	v_mul_f32_dpp v139, v139, v139 row_bcast:15 row_mask:0xa bank_mask:0xf
	v_mul_f32_dpp v140, v140, v140 row_bcast:15 row_mask:0xa bank_mask:0xf
	v_mul_f32_dpp v141, v141, v141 row_bcast:15 row_mask:0xa bank_mask:0xf
	v_mul_f32_dpp v142, v142, v142 row_bcast:15 row_mask:0xa bank_mask:0xf
	v_mul_f32_dpp v143, v143, v143 row_bcast:15 row_mask:0xa bank_mask:0xf
	v_mul_f32_dpp v144, v144, v144 row_bcast:15 row_mask:0xa bank_mask:0xf
	v_mul_f32_dpp v145, v145, v145 row_bcast:15 row_mask:0xa bank_mask:0xf
	s_add_u32 m0, s71, 3072
	s_nop 0
	global_load_lds_dwordx4 v232, s[14:15]
	v_mul_f32_dpp v146, v146, v146 row_bcast:15 row_mask:0xa bank_mask:0xf
	v_mul_f32_dpp v147, v147, v147 row_bcast:15 row_mask:0xa bank_mask:0xf
	v_mul_f32_dpp v148, v148, v148 row_bcast:15 row_mask:0xa bank_mask:0xf
	v_mul_f32_dpp v149, v149, v149 row_bcast:15 row_mask:0xa bank_mask:0xf
	v_mul_f32_dpp v150, v150, v150 row_bcast:15 row_mask:0xa bank_mask:0xf
	v_mul_f32_dpp v151, v151, v151 row_bcast:15 row_mask:0xa bank_mask:0xf
	v_mul_f32_dpp v152, v152, v152 row_bcast:15 row_mask:0xa bank_mask:0xf
	v_mul_f32_dpp v153, v153, v153 row_bcast:15 row_mask:0xa bank_mask:0xf
	v_mul_f32_dpp v154, v154, v154 row_bcast:15 row_mask:0xa bank_mask:0xf
	v_mul_f32_dpp v155, v155, v155 row_bcast:15 row_mask:0xa bank_mask:0xf
	v_mul_f32_dpp v156, v156, v156 row_bcast:15 row_mask:0xa bank_mask:0xf
	v_mul_f32_dpp v157, v157, v157 row_bcast:15 row_mask:0xa bank_mask:0xf
	v_mul_f32_dpp v158, v158, v158 row_bcast:15 row_mask:0xa bank_mask:0xf
	v_mul_f32_dpp v159, v159, v159 row_bcast:15 row_mask:0xa bank_mask:0xf
	v_mul_f32_dpp v128, v128, v128 row_bcast:31 row_mask:0xc bank_mask:0xf
	v_mul_f32_dpp v129, v129, v129 row_bcast:31 row_mask:0xc bank_mask:0xf
	v_mul_f32_dpp v130, v130, v130 row_bcast:31 row_mask:0xc bank_mask:0xf
	v_mul_f32_dpp v131, v131, v131 row_bcast:31 row_mask:0xc bank_mask:0xf
	v_mul_f32_dpp v132, v132, v132 row_bcast:31 row_mask:0xc bank_mask:0xf
	v_mul_f32_dpp v133, v133, v133 row_bcast:31 row_mask:0xc bank_mask:0xf
	v_mul_f32_dpp v134, v134, v134 row_bcast:31 row_mask:0xc bank_mask:0xf
	s_add_u32 m0, s71, 7168
	s_nop 0
	global_load_lds_dwordx4 v232, s[30:31]
	v_add_u32_e32 v228, s76, v228
	v_add_u32_e32 v230, s76, v230
	v_add_u32_e32 v231, s76, v231
	v_add_u32_e32 v232, s76, v232
	v_mul_f32_dpp v135, v135, v135 row_bcast:31 row_mask:0xc bank_mask:0xf
	v_mul_f32_dpp v136, v136, v136 row_bcast:31 row_mask:0xc bank_mask:0xf
	v_mul_f32_dpp v137, v137, v137 row_bcast:31 row_mask:0xc bank_mask:0xf
	v_mul_f32_dpp v138, v138, v138 row_bcast:31 row_mask:0xc bank_mask:0xf
	v_mul_f32_dpp v139, v139, v139 row_bcast:31 row_mask:0xc bank_mask:0xf
	v_mul_f32_dpp v140, v140, v140 row_bcast:31 row_mask:0xc bank_mask:0xf
	v_mul_f32_dpp v141, v141, v141 row_bcast:31 row_mask:0xc bank_mask:0xf
	v_mul_f32_dpp v142, v142, v142 row_bcast:31 row_mask:0xc bank_mask:0xf
	v_mul_f32_dpp v143, v143, v143 row_bcast:31 row_mask:0xc bank_mask:0xf
	v_mul_f32_dpp v144, v144, v144 row_bcast:31 row_mask:0xc bank_mask:0xf
	v_mul_f32_dpp v145, v145, v145 row_bcast:31 row_mask:0xc bank_mask:0xf
	v_mul_f32_dpp v146, v146, v146 row_bcast:31 row_mask:0xc bank_mask:0xf
	v_mul_f32_dpp v147, v147, v147 row_bcast:31 row_mask:0xc bank_mask:0xf
	v_mul_f32_dpp v148, v148, v148 row_bcast:31 row_mask:0xc bank_mask:0xf
	v_mul_f32_dpp v149, v149, v149 row_bcast:31 row_mask:0xc bank_mask:0xf
	v_mul_f32_dpp v150, v150, v150 row_bcast:31 row_mask:0xc bank_mask:0xf
	v_mul_f32_dpp v151, v151, v151 row_bcast:31 row_mask:0xc bank_mask:0xf
	v_mul_f32_dpp v152, v152, v152 row_bcast:31 row_mask:0xc bank_mask:0xf
	v_mul_f32_dpp v153, v153, v153 row_bcast:31 row_mask:0xc bank_mask:0xf
	v_mul_f32_dpp v154, v154, v154 row_bcast:31 row_mask:0xc bank_mask:0xf
	v_mul_f32_dpp v155, v155, v155 row_bcast:31 row_mask:0xc bank_mask:0xf
	v_mul_f32_dpp v156, v156, v156 row_bcast:31 row_mask:0xc bank_mask:0xf
	v_mul_f32_dpp v157, v157, v157 row_bcast:31 row_mask:0xc bank_mask:0xf
	v_mul_f32_dpp v158, v158, v158 row_bcast:31 row_mask:0xc bank_mask:0xf
	v_mul_f32_dpp v159, v159, v159 row_bcast:31 row_mask:0xc bank_mask:0xf
	s_mov_b32 exec_lo, 0
	s_brev_b32 exec_hi, 1
	ds_write_b128 v247, v[128:131] offset:0
	ds_write_b128 v247, v[132:135] offset:16
	ds_write_b128 v247, v[136:139] offset:32
	ds_write_b128 v247, v[140:143] offset:48
	ds_write_b128 v247, v[144:147] offset:64
	ds_write_b128 v247, v[148:151] offset:80
	ds_write_b128 v247, v[152:155] offset:96
	ds_write_b128 v247, v[156:159] offset:112
	s_mov_b64 exec, -1
	v_rcp_f32_e32 v220, v128
	v_rcp_f32_e32 v221, v129
	v_lshlrev_b32_e32 v218, 16, v0
	v_and_b32_e32 v219, 0xffff0000, v0
	v_pk_mul_f32 v[218:219], v[128:129], v[218:219]
	v_pk_mul_f32 v[220:221], v[220:221], v[96:97]
	v_cvt_pk_bf16_f32 v202, v218, v219
	v_cvt_pk_bf16_f32 v184, v220, v221
	v_rcp_f32_e32 v220, v130
	v_rcp_f32_e32 v221, v131
	v_lshlrev_b32_e32 v218, 16, v1
	v_and_b32_e32 v219, 0xffff0000, v1
	v_pk_mul_f32 v[218:219], v[130:131], v[218:219]
	v_pk_mul_f32 v[220:221], v[220:221], v[98:99]
	v_cvt_pk_bf16_f32 v203, v218, v219
	v_cvt_pk_bf16_f32 v185, v220, v221
	v_rcp_f32_e32 v220, v132
	v_rcp_f32_e32 v221, v133
	v_lshlrev_b32_e32 v218, 16, v2
	v_and_b32_e32 v219, 0xffff0000, v2
	v_pk_mul_f32 v[218:219], v[132:133], v[218:219]
	v_pk_mul_f32 v[220:221], v[220:221], v[100:101]
	v_cvt_pk_bf16_f32 v204, v218, v219
	v_cvt_pk_bf16_f32 v186, v220, v221
	v_rcp_f32_e32 v220, v134
	v_rcp_f32_e32 v221, v135
	v_lshlrev_b32_e32 v218, 16, v3
	v_and_b32_e32 v219, 0xffff0000, v3
	v_pk_mul_f32 v[218:219], v[134:135], v[218:219]
	v_pk_mul_f32 v[220:221], v[220:221], v[102:103]
	v_cvt_pk_bf16_f32 v205, v218, v219
	v_cvt_pk_bf16_f32 v187, v220, v221
	v_rcp_f32_e32 v220, v136
	v_rcp_f32_e32 v221, v137
	v_lshlrev_b32_e32 v218, 16, v4
	v_and_b32_e32 v219, 0xffff0000, v4
	v_pk_mul_f32 v[218:219], v[136:137], v[218:219]
	v_pk_mul_f32 v[220:221], v[220:221], v[104:105]
	v_cvt_pk_bf16_f32 v206, v218, v219
	v_cvt_pk_bf16_f32 v188, v220, v221
	v_rcp_f32_e32 v220, v138
	v_rcp_f32_e32 v221, v139
	v_lshlrev_b32_e32 v218, 16, v5
	v_and_b32_e32 v219, 0xffff0000, v5
	v_pk_mul_f32 v[218:219], v[138:139], v[218:219]
	v_pk_mul_f32 v[220:221], v[220:221], v[106:107]
	v_cvt_pk_bf16_f32 v207, v218, v219
	v_cvt_pk_bf16_f32 v189, v220, v221
	v_rcp_f32_e32 v220, v140
	v_rcp_f32_e32 v221, v141
	v_lshlrev_b32_e32 v218, 16, v6
	v_and_b32_e32 v219, 0xffff0000, v6
	v_pk_mul_f32 v[218:219], v[140:141], v[218:219]
	v_pk_mul_f32 v[220:221], v[220:221], v[108:109]
	v_cvt_pk_bf16_f32 v208, v218, v219
	v_cvt_pk_bf16_f32 v190, v220, v221
	v_rcp_f32_e32 v220, v142
	v_rcp_f32_e32 v221, v143
	v_lshlrev_b32_e32 v218, 16, v7
	v_and_b32_e32 v219, 0xffff0000, v7
	v_pk_mul_f32 v[218:219], v[142:143], v[218:219]
	v_pk_mul_f32 v[220:221], v[220:221], v[110:111]
	v_cvt_pk_bf16_f32 v209, v218, v219
	v_cvt_pk_bf16_f32 v191, v220, v221
	v_rcp_f32_e32 v220, v144
	v_rcp_f32_e32 v221, v145
	v_lshlrev_b32_e32 v218, 16, v8
	v_and_b32_e32 v219, 0xffff0000, v8
	v_pk_mul_f32 v[218:219], v[144:145], v[218:219]
	v_pk_mul_f32 v[220:221], v[220:221], v[112:113]
	v_cvt_pk_bf16_f32 v210, v218, v219
	v_cvt_pk_bf16_f32 v192, v220, v221
	v_rcp_f32_e32 v220, v146
	v_rcp_f32_e32 v221, v147
	v_lshlrev_b32_e32 v218, 16, v9
	v_and_b32_e32 v219, 0xffff0000, v9
	v_pk_mul_f32 v[218:219], v[146:147], v[218:219]
	v_pk_mul_f32 v[220:221], v[220:221], v[114:115]
	v_cvt_pk_bf16_f32 v211, v218, v219
	v_cvt_pk_bf16_f32 v193, v220, v221
	v_rcp_f32_e32 v220, v148
	v_rcp_f32_e32 v221, v149
	v_lshlrev_b32_e32 v218, 16, v10
	v_and_b32_e32 v219, 0xffff0000, v10
	v_pk_mul_f32 v[218:219], v[148:149], v[218:219]
	v_pk_mul_f32 v[220:221], v[220:221], v[116:117]
	v_cvt_pk_bf16_f32 v212, v218, v219
	v_cvt_pk_bf16_f32 v194, v220, v221
	v_rcp_f32_e32 v220, v150
	v_rcp_f32_e32 v221, v151
	v_lshlrev_b32_e32 v218, 16, v11
	v_and_b32_e32 v219, 0xffff0000, v11
	v_pk_mul_f32 v[218:219], v[150:151], v[218:219]
	v_pk_mul_f32 v[220:221], v[220:221], v[118:119]
	v_cvt_pk_bf16_f32 v213, v218, v219
	v_cvt_pk_bf16_f32 v195, v220, v221
	v_rcp_f32_e32 v220, v152
	v_rcp_f32_e32 v221, v153
	v_lshlrev_b32_e32 v218, 16, v12
	v_and_b32_e32 v219, 0xffff0000, v12
	v_pk_mul_f32 v[218:219], v[152:153], v[218:219]
	v_pk_mul_f32 v[220:221], v[220:221], v[120:121]
	v_cvt_pk_bf16_f32 v214, v218, v219
	v_cvt_pk_bf16_f32 v196, v220, v221
	v_rcp_f32_e32 v220, v154
	v_rcp_f32_e32 v221, v155
	v_lshlrev_b32_e32 v218, 16, v13
	v_and_b32_e32 v219, 0xffff0000, v13
	v_pk_mul_f32 v[218:219], v[154:155], v[218:219]
	v_pk_mul_f32 v[220:221], v[220:221], v[122:123]
	v_cvt_pk_bf16_f32 v215, v218, v219
	v_cvt_pk_bf16_f32 v197, v220, v221
	v_rcp_f32_e32 v220, v156
	v_rcp_f32_e32 v221, v157
	v_lshlrev_b32_e32 v218, 16, v14
	v_and_b32_e32 v219, 0xffff0000, v14
	v_pk_mul_f32 v[218:219], v[156:157], v[218:219]
	v_pk_mul_f32 v[220:221], v[220:221], v[124:125]
	v_cvt_pk_bf16_f32 v216, v218, v219
	v_cvt_pk_bf16_f32 v198, v220, v221
	v_rcp_f32_e32 v220, v158
	v_rcp_f32_e32 v221, v159
	v_lshlrev_b32_e32 v218, 16, v15
	v_and_b32_e32 v219, 0xffff0000, v15
	v_pk_mul_f32 v[218:219], v[158:159], v[218:219]
	v_pk_mul_f32 v[220:221], v[220:221], v[126:127]
	v_cvt_pk_bf16_f32 v217, v218, v219
	v_cvt_pk_bf16_f32 v199, v220, v221
	ds_write_b128 v222, v[184:187] offset:1024
	ds_write_b128 v223, v[188:191] offset:1024
	ds_write_b128 v224, v[192:195] offset:1024
	ds_write_b128 v225, v[196:199] offset:1024
	ds_write_b128 v226, v[202:205]
	ds_write_b128 v226, v[206:209] offset:16
	ds_write_b128 v226, v[210:213] offset:32
	ds_write_b128 v226, v[214:217] offset:48
	s_waitcnt lgkmcnt(0)
	s_barrier
	s_waitcnt vmcnt(0)
	ds_read_b128 v[234:237], v248
	ds_read_b128 v[238:241], v249
	ds_read_b128 v[242:245], v250
	ds_read_b128 v[168:171], v251
	ds_read_b128 v[0:3], v248 offset:4096
	ds_read_b128 v[4:7], v249 offset:4096
	ds_read_b128 v[8:11], v250 offset:4096
	ds_read_b128 v[12:15], v251 offset:4096
	s_cmp_eq_u32 s70, 31
	s_cselect_b32 s76, 0, s33
	s_add_u32 s1, s72, s77
	s_add_u32 s77, s77, 0x4000
	s_cmp_eq_u32 s77, 0x10400
	s_cselect_b32 s77, 0x24000, s77
	s_cmp_eq_u32 s77, 0x28000
	s_cselect_b32 s77, 0x8400, s77
	s_waitcnt lgkmcnt(4)
	s_add_u32 m0, s1, 0
	s_nop 0
	global_load_lds_dwordx4 v252, s[34:35]
	v_lshlrev_b32_e32 v96, 16, v234
	v_and_b32_e32 v97, 0xffff0000, v234
	v_lshlrev_b32_e32 v98, 16, v235
	v_and_b32_e32 v99, 0xffff0000, v235
	v_lshlrev_b32_e32 v100, 16, v236
	v_and_b32_e32 v101, 0xffff0000, v236
	v_lshlrev_b32_e32 v102, 16, v237
	v_and_b32_e32 v103, 0xffff0000, v237
	v_lshlrev_b32_e32 v104, 16, v238
	v_and_b32_e32 v105, 0xffff0000, v238
	v_lshlrev_b32_e32 v106, 16, v239
	v_and_b32_e32 v107, 0xffff0000, v239
	v_lshlrev_b32_e32 v108, 16, v240
	v_and_b32_e32 v109, 0xffff0000, v240
	v_lshlrev_b32_e32 v110, 16, v241
	v_and_b32_e32 v111, 0xffff0000, v241
	v_lshlrev_b32_e32 v112, 16, v242
	v_and_b32_e32 v113, 0xffff0000, v242
	v_lshlrev_b32_e32 v114, 16, v243
	v_and_b32_e32 v115, 0xffff0000, v243
	v_lshlrev_b32_e32 v116, 16, v244
	s_add_u32 m0, s1, 1024
	s_nop 0
	global_load_lds_dwordx4 v253, s[34:35]
	v_and_b32_e32 v117, 0xffff0000, v244
	v_lshlrev_b32_e32 v118, 16, v245
	v_and_b32_e32 v119, 0xffff0000, v245
	v_lshlrev_b32_e32 v120, 16, v168
	v_and_b32_e32 v121, 0xffff0000, v168
	v_lshlrev_b32_e32 v122, 16, v169
	v_and_b32_e32 v123, 0xffff0000, v169
	v_lshlrev_b32_e32 v124, 16, v170
	v_and_b32_e32 v125, 0xffff0000, v170
	v_lshlrev_b32_e32 v126, 16, v171
	v_and_b32_e32 v127, 0xffff0000, v171
	s_waitcnt lgkmcnt(0)
	v_sub_f32_e32 v128, 1.0, v96
	v_sub_f32_e32 v129, 1.0, v97
	v_sub_f32_e32 v130, 1.0, v98
	v_sub_f32_e32 v131, 1.0, v99
	v_sub_f32_e32 v132, 1.0, v100
	v_sub_f32_e32 v133, 1.0, v101
	v_sub_f32_e32 v134, 1.0, v102
	v_sub_f32_e32 v135, 1.0, v103
	v_sub_f32_e32 v136, 1.0, v104
	v_sub_f32_e32 v137, 1.0, v105
	s_add_u32 m0, s1, 2048
	s_nop 0
	global_load_lds_dwordx4 v254, s[34:35]
	v_sub_f32_e32 v138, 1.0, v106
	v_sub_f32_e32 v139, 1.0, v107
	v_sub_f32_e32 v140, 1.0, v108
	v_sub_f32_e32 v141, 1.0, v109
	v_sub_f32_e32 v142, 1.0, v110
	v_sub_f32_e32 v143, 1.0, v111
	v_sub_f32_e32 v144, 1.0, v112
	v_sub_f32_e32 v145, 1.0, v113
	v_sub_f32_e32 v146, 1.0, v114
	v_sub_f32_e32 v147, 1.0, v115
	v_sub_f32_e32 v148, 1.0, v116
	v_sub_f32_e32 v149, 1.0, v117
	v_sub_f32_e32 v150, 1.0, v118
	v_sub_f32_e32 v151, 1.0, v119
	v_sub_f32_e32 v152, 1.0, v120
	v_sub_f32_e32 v153, 1.0, v121
	v_sub_f32_e32 v154, 1.0, v122
	v_sub_f32_e32 v155, 1.0, v123
	v_sub_f32_e32 v156, 1.0, v124
	v_sub_f32_e32 v157, 1.0, v125
	v_sub_f32_e32 v158, 1.0, v126
	s_add_u32 m0, s1, 3072
	s_nop 0
	global_load_lds_dwordx4 v255, s[34:35]
	v_add_u32_e32 v252, s76, v252
	v_add_u32_e32 v253, s76, v253
	v_add_u32_e32 v254, s76, v254
	v_add_u32_e32 v255, s76, v255
	v_sub_f32_e32 v159, 1.0, v127
	v_mul_f32_dpp v128, v128, v128 row_shr:1 row_mask:0xf bank_mask:0xf
	v_mul_f32_dpp v129, v129, v129 row_shr:1 row_mask:0xf bank_mask:0xf
	v_mul_f32_dpp v130, v130, v130 row_shr:1 row_mask:0xf bank_mask:0xf
	v_mul_f32_dpp v131, v131, v131 row_shr:1 row_mask:0xf bank_mask:0xf
	v_mul_f32_dpp v132, v132, v132 row_shr:1 row_mask:0xf bank_mask:0xf
	v_mul_f32_dpp v133, v133, v133 row_shr:1 row_mask:0xf bank_mask:0xf
	v_mul_f32_dpp v134, v134, v134 row_shr:1 row_mask:0xf bank_mask:0xf
	v_mul_f32_dpp v135, v135, v135 row_shr:1 row_mask:0xf bank_mask:0xf
	v_mul_f32_dpp v136, v136, v136 row_shr:1 row_mask:0xf bank_mask:0xf
	v_mul_f32_dpp v137, v137, v137 row_shr:1 row_mask:0xf bank_mask:0xf
	v_mul_f32_dpp v138, v138, v138 row_shr:1 row_mask:0xf bank_mask:0xf
	v_mul_f32_dpp v139, v139, v139 row_shr:1 row_mask:0xf bank_mask:0xf
	v_mul_f32_dpp v140, v140, v140 row_shr:1 row_mask:0xf bank_mask:0xf
	v_mul_f32_dpp v141, v141, v141 row_shr:1 row_mask:0xf bank_mask:0xf
	v_mul_f32_dpp v142, v142, v142 row_shr:1 row_mask:0xf bank_mask:0xf
	v_mul_f32_dpp v143, v143, v143 row_shr:1 row_mask:0xf bank_mask:0xf
	v_mul_f32_dpp v144, v144, v144 row_shr:1 row_mask:0xf bank_mask:0xf
	v_mul_f32_dpp v145, v145, v145 row_shr:1 row_mask:0xf bank_mask:0xf
	v_mul_f32_dpp v146, v146, v146 row_shr:1 row_mask:0xf bank_mask:0xf
	v_mul_f32_dpp v147, v147, v147 row_shr:1 row_mask:0xf bank_mask:0xf
	s_add_u32 m0, s71, 0
	s_nop 0
	global_load_lds_dwordx4 v228, s[14:15]
	v_mul_f32_dpp v148, v148, v148 row_shr:1 row_mask:0xf bank_mask:0xf
	v_mul_f32_dpp v149, v149, v149 row_shr:1 row_mask:0xf bank_mask:0xf
	v_mul_f32_dpp v150, v150, v150 row_shr:1 row_mask:0xf bank_mask:0xf
	v_mul_f32_dpp v151, v151, v151 row_shr:1 row_mask:0xf bank_mask:0xf
	v_mul_f32_dpp v152, v152, v152 row_shr:1 row_mask:0xf bank_mask:0xf
	v_mul_f32_dpp v153, v153, v153 row_shr:1 row_mask:0xf bank_mask:0xf
	v_mul_f32_dpp v154, v154, v154 row_shr:1 row_mask:0xf bank_mask:0xf
	v_mul_f32_dpp v155, v155, v155 row_shr:1 row_mask:0xf bank_mask:0xf
	v_mul_f32_dpp v156, v156, v156 row_shr:1 row_mask:0xf bank_mask:0xf
	v_mul_f32_dpp v157, v157, v157 row_shr:1 row_mask:0xf bank_mask:0xf
	v_mul_f32_dpp v158, v158, v158 row_shr:1 row_mask:0xf bank_mask:0xf
	v_mul_f32_dpp v159, v159, v159 row_shr:1 row_mask:0xf bank_mask:0xf
	v_mul_f32_dpp v128, v128, v128 row_shr:2 row_mask:0xf bank_mask:0xf
	v_mul_f32_dpp v129, v129, v129 row_shr:2 row_mask:0xf bank_mask:0xf
	v_mul_f32_dpp v130, v130, v130 row_shr:2 row_mask:0xf bank_mask:0xf
	v_mul_f32_dpp v131, v131, v131 row_shr:2 row_mask:0xf bank_mask:0xf
	v_mul_f32_dpp v132, v132, v132 row_shr:2 row_mask:0xf bank_mask:0xf
	v_mul_f32_dpp v133, v133, v133 row_shr:2 row_mask:0xf bank_mask:0xf
	v_mul_f32_dpp v134, v134, v134 row_shr:2 row_mask:0xf bank_mask:0xf
	v_mul_f32_dpp v135, v135, v135 row_shr:2 row_mask:0xf bank_mask:0xf
	v_mul_f32_dpp v136, v136, v136 row_shr:2 row_mask:0xf bank_mask:0xf
	s_add_u32 m0, s71, 4096
	s_nop 0
	global_load_lds_dwordx4 v228, s[30:31]
	v_mul_f32_dpp v137, v137, v137 row_shr:2 row_mask:0xf bank_mask:0xf
	v_mul_f32_dpp v138, v138, v138 row_shr:2 row_mask:0xf bank_mask:0xf
	v_mul_f32_dpp v139, v139, v139 row_shr:2 row_mask:0xf bank_mask:0xf
	v_mul_f32_dpp v140, v140, v140 row_shr:2 row_mask:0xf bank_mask:0xf
	v_mul_f32_dpp v141, v141, v141 row_shr:2 row_mask:0xf bank_mask:0xf
	v_mul_f32_dpp v142, v142, v142 row_shr:2 row_mask:0xf bank_mask:0xf
	v_mul_f32_dpp v143, v143, v143 row_shr:2 row_mask:0xf bank_mask:0xf
	v_mul_f32_dpp v144, v144, v144 row_shr:2 row_mask:0xf bank_mask:0xf
	v_mul_f32_dpp v145, v145, v145 row_shr:2 row_mask:0xf bank_mask:0xf
	v_mul_f32_dpp v146, v146, v146 row_shr:2 row_mask:0xf bank_mask:0xf
	v_mul_f32_dpp v147, v147, v147 row_shr:2 row_mask:0xf bank_mask:0xf
	v_mul_f32_dpp v148, v148, v148 row_shr:2 row_mask:0xf bank_mask:0xf
	v_mul_f32_dpp v149, v149, v149 row_shr:2 row_mask:0xf bank_mask:0xf
	v_mul_f32_dpp v150, v150, v150 row_shr:2 row_mask:0xf bank_mask:0xf
	v_mul_f32_dpp v151, v151, v151 row_shr:2 row_mask:0xf bank_mask:0xf
	v_mul_f32_dpp v152, v152, v152 row_shr:2 row_mask:0xf bank_mask:0xf
	v_mul_f32_dpp v153, v153, v153 row_shr:2 row_mask:0xf bank_mask:0xf
	v_mul_f32_dpp v154, v154, v154 row_shr:2 row_mask:0xf bank_mask:0xf
	v_mul_f32_dpp v155, v155, v155 row_shr:2 row_mask:0xf bank_mask:0xf
	v_mul_f32_dpp v156, v156, v156 row_shr:2 row_mask:0xf bank_mask:0xf
	v_mul_f32_dpp v157, v157, v157 row_shr:2 row_mask:0xf bank_mask:0xf
	s_add_u32 m0, s71, 1024
	s_nop 0
	global_load_lds_dwordx4 v230, s[14:15]
	v_mul_f32_dpp v158, v158, v158 row_shr:2 row_mask:0xf bank_mask:0xf
	v_mul_f32_dpp v159, v159, v159 row_shr:2 row_mask:0xf bank_mask:0xf
	v_mul_f32_dpp v128, v128, v128 row_shr:4 row_mask:0xf bank_mask:0xf
	v_mul_f32_dpp v129, v129, v129 row_shr:4 row_mask:0xf bank_mask:0xf
	v_mul_f32_dpp v130, v130, v130 row_shr:4 row_mask:0xf bank_mask:0xf
	v_mul_f32_dpp v131, v131, v131 row_shr:4 row_mask:0xf bank_mask:0xf
	v_mul_f32_dpp v132, v132, v132 row_shr:4 row_mask:0xf bank_mask:0xf
	v_mul_f32_dpp v133, v133, v133 row_shr:4 row_mask:0xf bank_mask:0xf
	v_mul_f32_dpp v134, v134, v134 row_shr:4 row_mask:0xf bank_mask:0xf
	v_mul_f32_dpp v135, v135, v135 row_shr:4 row_mask:0xf bank_mask:0xf
	v_mul_f32_dpp v136, v136, v136 row_shr:4 row_mask:0xf bank_mask:0xf
	v_mul_f32_dpp v137, v137, v137 row_shr:4 row_mask:0xf bank_mask:0xf
	v_mul_f32_dpp v138, v138, v138 row_shr:4 row_mask:0xf bank_mask:0xf
	v_mul_f32_dpp v139, v139, v139 row_shr:4 row_mask:0xf bank_mask:0xf
	v_mul_f32_dpp v140, v140, v140 row_shr:4 row_mask:0xf bank_mask:0xf
	v_mul_f32_dpp v141, v141, v141 row_shr:4 row_mask:0xf bank_mask:0xf
	v_mul_f32_dpp v142, v142, v142 row_shr:4 row_mask:0xf bank_mask:0xf
	v_mul_f32_dpp v143, v143, v143 row_shr:4 row_mask:0xf bank_mask:0xf
	v_mul_f32_dpp v144, v144, v144 row_shr:4 row_mask:0xf bank_mask:0xf
	v_mul_f32_dpp v145, v145, v145 row_shr:4 row_mask:0xf bank_mask:0xf
	v_mul_f32_dpp v146, v146, v146 row_shr:4 row_mask:0xf bank_mask:0xf
	s_add_u32 m0, s71, 5120
	s_nop 0
	global_load_lds_dwordx4 v230, s[30:31]
	v_mul_f32_dpp v147, v147, v147 row_shr:4 row_mask:0xf bank_mask:0xf
	v_mul_f32_dpp v148, v148, v148 row_shr:4 row_mask:0xf bank_mask:0xf
	v_mul_f32_dpp v149, v149, v149 row_shr:4 row_mask:0xf bank_mask:0xf
	v_mul_f32_dpp v150, v150, v150 row_shr:4 row_mask:0xf bank_mask:0xf
	v_mul_f32_dpp v151, v151, v151 row_shr:4 row_mask:0xf bank_mask:0xf
	v_mul_f32_dpp v152, v152, v152 row_shr:4 row_mask:0xf bank_mask:0xf
	v_mul_f32_dpp v153, v153, v153 row_shr:4 row_mask:0xf bank_mask:0xf
	v_mul_f32_dpp v154, v154, v154 row_shr:4 row_mask:0xf bank_mask:0xf
	v_mul_f32_dpp v155, v155, v155 row_shr:4 row_mask:0xf bank_mask:0xf
	v_mul_f32_dpp v156, v156, v156 row_shr:4 row_mask:0xf bank_mask:0xf
	v_mul_f32_dpp v157, v157, v157 row_shr:4 row_mask:0xf bank_mask:0xf
	v_mul_f32_dpp v158, v158, v158 row_shr:4 row_mask:0xf bank_mask:0xf
	v_mul_f32_dpp v159, v159, v159 row_shr:4 row_mask:0xf bank_mask:0xf
	v_mul_f32_dpp v128, v128, v128 row_shr:8 row_mask:0xf bank_mask:0xf
	v_mul_f32_dpp v129, v129, v129 row_shr:8 row_mask:0xf bank_mask:0xf
	v_mul_f32_dpp v130, v130, v130 row_shr:8 row_mask:0xf bank_mask:0xf
	v_mul_f32_dpp v131, v131, v131 row_shr:8 row_mask:0xf bank_mask:0xf
	v_mul_f32_dpp v132, v132, v132 row_shr:8 row_mask:0xf bank_mask:0xf
	v_mul_f32_dpp v133, v133, v133 row_shr:8 row_mask:0xf bank_mask:0xf
	v_mul_f32_dpp v134, v134, v134 row_shr:8 row_mask:0xf bank_mask:0xf
	v_mul_f32_dpp v135, v135, v135 row_shr:8 row_mask:0xf bank_mask:0xf
	s_add_u32 m0, s71, 2048
	s_nop 0
	global_load_lds_dwordx4 v231, s[14:15]
	v_mul_f32_dpp v136, v136, v136 row_shr:8 row_mask:0xf bank_mask:0xf
	v_mul_f32_dpp v137, v137, v137 row_shr:8 row_mask:0xf bank_mask:0xf
	v_mul_f32_dpp v138, v138, v138 row_shr:8 row_mask:0xf bank_mask:0xf
	v_mul_f32_dpp v139, v139, v139 row_shr:8 row_mask:0xf bank_mask:0xf
	v_mul_f32_dpp v140, v140, v140 row_shr:8 row_mask:0xf bank_mask:0xf
	v_mul_f32_dpp v141, v141, v141 row_shr:8 row_mask:0xf bank_mask:0xf
	v_mul_f32_dpp v142, v142, v142 row_shr:8 row_mask:0xf bank_mask:0xf
	v_mul_f32_dpp v143, v143, v143 row_shr:8 row_mask:0xf bank_mask:0xf
	v_mul_f32_dpp v144, v144, v144 row_shr:8 row_mask:0xf bank_mask:0xf
	v_mul_f32_dpp v145, v145, v145 row_shr:8 row_mask:0xf bank_mask:0xf
	v_mul_f32_dpp v146, v146, v146 row_shr:8 row_mask:0xf bank_mask:0xf
	v_mul_f32_dpp v147, v147, v147 row_shr:8 row_mask:0xf bank_mask:0xf
	v_mul_f32_dpp v148, v148, v148 row_shr:8 row_mask:0xf bank_mask:0xf
	v_mul_f32_dpp v149, v149, v149 row_shr:8 row_mask:0xf bank_mask:0xf
	v_mul_f32_dpp v150, v150, v150 row_shr:8 row_mask:0xf bank_mask:0xf
	v_mul_f32_dpp v151, v151, v151 row_shr:8 row_mask:0xf bank_mask:0xf
	v_mul_f32_dpp v152, v152, v152 row_shr:8 row_mask:0xf bank_mask:0xf
	v_mul_f32_dpp v153, v153, v153 row_shr:8 row_mask:0xf bank_mask:0xf
	v_mul_f32_dpp v154, v154, v154 row_shr:8 row_mask:0xf bank_mask:0xf
	v_mul_f32_dpp v155, v155, v155 row_shr:8 row_mask:0xf bank_mask:0xf
	v_mul_f32_dpp v156, v156, v156 row_shr:8 row_mask:0xf bank_mask:0xf
	s_add_u32 m0, s71, 6144
	s_nop 0
	global_load_lds_dwordx4 v231, s[30:31]
	v_mul_f32_dpp v157, v157, v157 row_shr:8 row_mask:0xf bank_mask:0xf
	v_mul_f32_dpp v158, v158, v158 row_shr:8 row_mask:0xf bank_mask:0xf
	v_mul_f32_dpp v159, v159, v159 row_shr:8 row_mask:0xf bank_mask:0xf
	v_mul_f32_dpp v128, v128, v128 row_bcast:15 row_mask:0xa bank_mask:0xf
	v_mul_f32_dpp v129, v129, v129 row_bcast:15 row_mask:0xa bank_mask:0xf
	v_mul_f32_dpp v130, v130, v130 row_bcast:15 row_mask:0xa bank_mask:0xf
	v_mul_f32_dpp v131, v131, v131 row_bcast:15 row_mask:0xa bank_mask:0xf
	v_mul_f32_dpp v132, v132, v132 row_bcast:15 row_mask:0xa bank_mask:0xf
	v_mul_f32_dpp v133, v133, v133 row_bcast:15 row_mask:0xa bank_mask:0xf
	v_mul_f32_dpp v134, v134, v134 row_bcast:15 row_mask:0xa bank_mask:0xf
	v_mul_f32_dpp v135, v135, v135 row_bcast:15 row_mask:0xa bank_mask:0xf
	v_mul_f32_dpp v136, v136, v136 row_bcast:15 row_mask:0xa bank_mask:0xf
	v_mul_f32_dpp v137, v137, v137 row_bcast:15 row_mask:0xa bank_mask:0xf
	v_mul_f32_dpp v138, v138, v138 row_bcast:15 row_mask:0xa bank_mask:0xf
	v_mul_f32_dpp v139, v139, v139 row_bcast:15 row_mask:0xa bank_mask:0xf
	v_mul_f32_dpp v140, v140, v140 row_bcast:15 row_mask:0xa bank_mask:0xf
	v_mul_f32_dpp v141, v141, v141 row_bcast:15 row_mask:0xa bank_mask:0xf
	v_mul_f32_dpp v142, v142, v142 row_bcast:15 row_mask:0xa bank_mask:0xf
	v_mul_f32_dpp v143, v143, v143 row_bcast:15 row_mask:0xa bank_mask:0xf
	v_mul_f32_dpp v144, v144, v144 row_bcast:15 row_mask:0xa bank_mask:0xf
	v_mul_f32_dpp v145, v145, v145 row_bcast:15 row_mask:0xa bank_mask:0xf
	s_add_u32 m0, s71, 3072
	s_nop 0
	global_load_lds_dwordx4 v232, s[14:15]
	v_mul_f32_dpp v146, v146, v146 row_bcast:15 row_mask:0xa bank_mask:0xf
	v_mul_f32_dpp v147, v147, v147 row_bcast:15 row_mask:0xa bank_mask:0xf
	v_mul_f32_dpp v148, v148, v148 row_bcast:15 row_mask:0xa bank_mask:0xf
	v_mul_f32_dpp v149, v149, v149 row_bcast:15 row_mask:0xa bank_mask:0xf
	v_mul_f32_dpp v150, v150, v150 row_bcast:15 row_mask:0xa bank_mask:0xf
	v_mul_f32_dpp v151, v151, v151 row_bcast:15 row_mask:0xa bank_mask:0xf
	v_mul_f32_dpp v152, v152, v152 row_bcast:15 row_mask:0xa bank_mask:0xf
	v_mul_f32_dpp v153, v153, v153 row_bcast:15 row_mask:0xa bank_mask:0xf
	v_mul_f32_dpp v154, v154, v154 row_bcast:15 row_mask:0xa bank_mask:0xf
	v_mul_f32_dpp v155, v155, v155 row_bcast:15 row_mask:0xa bank_mask:0xf
	v_mul_f32_dpp v156, v156, v156 row_bcast:15 row_mask:0xa bank_mask:0xf
	v_mul_f32_dpp v157, v157, v157 row_bcast:15 row_mask:0xa bank_mask:0xf
	v_mul_f32_dpp v158, v158, v158 row_bcast:15 row_mask:0xa bank_mask:0xf
	v_mul_f32_dpp v159, v159, v159 row_bcast:15 row_mask:0xa bank_mask:0xf
	v_mul_f32_dpp v128, v128, v128 row_bcast:31 row_mask:0xc bank_mask:0xf
	v_mul_f32_dpp v129, v129, v129 row_bcast:31 row_mask:0xc bank_mask:0xf
	v_mul_f32_dpp v130, v130, v130 row_bcast:31 row_mask:0xc bank_mask:0xf
	v_mul_f32_dpp v131, v131, v131 row_bcast:31 row_mask:0xc bank_mask:0xf
	v_mul_f32_dpp v132, v132, v132 row_bcast:31 row_mask:0xc bank_mask:0xf
	v_mul_f32_dpp v133, v133, v133 row_bcast:31 row_mask:0xc bank_mask:0xf
	v_mul_f32_dpp v134, v134, v134 row_bcast:31 row_mask:0xc bank_mask:0xf
	s_add_u32 m0, s71, 7168
	s_nop 0
	global_load_lds_dwordx4 v232, s[30:31]
	v_add_u32_e32 v228, s76, v228
	v_add_u32_e32 v230, s76, v230
	v_add_u32_e32 v231, s76, v231
	v_add_u32_e32 v232, s76, v232
	v_mul_f32_dpp v135, v135, v135 row_bcast:31 row_mask:0xc bank_mask:0xf
	v_mul_f32_dpp v136, v136, v136 row_bcast:31 row_mask:0xc bank_mask:0xf
	v_mul_f32_dpp v137, v137, v137 row_bcast:31 row_mask:0xc bank_mask:0xf
	v_mul_f32_dpp v138, v138, v138 row_bcast:31 row_mask:0xc bank_mask:0xf
	v_mul_f32_dpp v139, v139, v139 row_bcast:31 row_mask:0xc bank_mask:0xf
	v_mul_f32_dpp v140, v140, v140 row_bcast:31 row_mask:0xc bank_mask:0xf
	v_mul_f32_dpp v141, v141, v141 row_bcast:31 row_mask:0xc bank_mask:0xf
	v_mul_f32_dpp v142, v142, v142 row_bcast:31 row_mask:0xc bank_mask:0xf
	v_mul_f32_dpp v143, v143, v143 row_bcast:31 row_mask:0xc bank_mask:0xf
	v_mul_f32_dpp v144, v144, v144 row_bcast:31 row_mask:0xc bank_mask:0xf
	v_mul_f32_dpp v145, v145, v145 row_bcast:31 row_mask:0xc bank_mask:0xf
	v_mul_f32_dpp v146, v146, v146 row_bcast:31 row_mask:0xc bank_mask:0xf
	v_mul_f32_dpp v147, v147, v147 row_bcast:31 row_mask:0xc bank_mask:0xf
	v_mul_f32_dpp v148, v148, v148 row_bcast:31 row_mask:0xc bank_mask:0xf
	v_mul_f32_dpp v149, v149, v149 row_bcast:31 row_mask:0xc bank_mask:0xf
	v_mul_f32_dpp v150, v150, v150 row_bcast:31 row_mask:0xc bank_mask:0xf
	v_mul_f32_dpp v151, v151, v151 row_bcast:31 row_mask:0xc bank_mask:0xf
	v_mul_f32_dpp v152, v152, v152 row_bcast:31 row_mask:0xc bank_mask:0xf
	v_mul_f32_dpp v153, v153, v153 row_bcast:31 row_mask:0xc bank_mask:0xf
	v_mul_f32_dpp v154, v154, v154 row_bcast:31 row_mask:0xc bank_mask:0xf
	v_mul_f32_dpp v155, v155, v155 row_bcast:31 row_mask:0xc bank_mask:0xf
	v_mul_f32_dpp v156, v156, v156 row_bcast:31 row_mask:0xc bank_mask:0xf
	v_mul_f32_dpp v157, v157, v157 row_bcast:31 row_mask:0xc bank_mask:0xf
	v_mul_f32_dpp v158, v158, v158 row_bcast:31 row_mask:0xc bank_mask:0xf
	v_mul_f32_dpp v159, v159, v159 row_bcast:31 row_mask:0xc bank_mask:0xf
	s_mov_b32 exec_lo, 0
	s_brev_b32 exec_hi, 1
	ds_write_b128 v247, v[128:131] offset:512
	ds_write_b128 v247, v[132:135] offset:528
	ds_write_b128 v247, v[136:139] offset:544
	ds_write_b128 v247, v[140:143] offset:560
	ds_write_b128 v247, v[144:147] offset:576
	ds_write_b128 v247, v[148:151] offset:592
	ds_write_b128 v247, v[152:155] offset:608
	ds_write_b128 v247, v[156:159] offset:624
	s_mov_b64 exec, -1
	v_rcp_f32_e32 v220, v128
	v_rcp_f32_e32 v221, v129
	v_lshlrev_b32_e32 v218, 16, v0
	v_and_b32_e32 v219, 0xffff0000, v0
	v_pk_mul_f32 v[218:219], v[128:129], v[218:219]
	v_pk_mul_f32 v[220:221], v[220:221], v[96:97]
	v_cvt_pk_bf16_f32 v202, v218, v219
	v_cvt_pk_bf16_f32 v184, v220, v221
	v_rcp_f32_e32 v220, v130
	v_rcp_f32_e32 v221, v131
	v_lshlrev_b32_e32 v218, 16, v1
	v_and_b32_e32 v219, 0xffff0000, v1
	v_pk_mul_f32 v[218:219], v[130:131], v[218:219]
	v_pk_mul_f32 v[220:221], v[220:221], v[98:99]
	v_cvt_pk_bf16_f32 v203, v218, v219
	v_cvt_pk_bf16_f32 v185, v220, v221
	v_rcp_f32_e32 v220, v132
	v_rcp_f32_e32 v221, v133
	v_lshlrev_b32_e32 v218, 16, v2
	v_and_b32_e32 v219, 0xffff0000, v2
	v_pk_mul_f32 v[218:219], v[132:133], v[218:219]
	v_pk_mul_f32 v[220:221], v[220:221], v[100:101]
	v_cvt_pk_bf16_f32 v204, v218, v219
	v_cvt_pk_bf16_f32 v186, v220, v221
	v_rcp_f32_e32 v220, v134
	v_rcp_f32_e32 v221, v135
	v_lshlrev_b32_e32 v218, 16, v3
	v_and_b32_e32 v219, 0xffff0000, v3
	v_pk_mul_f32 v[218:219], v[134:135], v[218:219]
	v_pk_mul_f32 v[220:221], v[220:221], v[102:103]
	v_cvt_pk_bf16_f32 v205, v218, v219
	v_cvt_pk_bf16_f32 v187, v220, v221
	v_rcp_f32_e32 v220, v136
	v_rcp_f32_e32 v221, v137
	v_lshlrev_b32_e32 v218, 16, v4
	v_and_b32_e32 v219, 0xffff0000, v4
	v_pk_mul_f32 v[218:219], v[136:137], v[218:219]
	v_pk_mul_f32 v[220:221], v[220:221], v[104:105]
	v_cvt_pk_bf16_f32 v206, v218, v219
	v_cvt_pk_bf16_f32 v188, v220, v221
	v_rcp_f32_e32 v220, v138
	v_rcp_f32_e32 v221, v139
	v_lshlrev_b32_e32 v218, 16, v5
	v_and_b32_e32 v219, 0xffff0000, v5
	v_pk_mul_f32 v[218:219], v[138:139], v[218:219]
	v_pk_mul_f32 v[220:221], v[220:221], v[106:107]
	v_cvt_pk_bf16_f32 v207, v218, v219
	v_cvt_pk_bf16_f32 v189, v220, v221
	v_rcp_f32_e32 v220, v140
	v_rcp_f32_e32 v221, v141
	v_lshlrev_b32_e32 v218, 16, v6
	v_and_b32_e32 v219, 0xffff0000, v6
	v_pk_mul_f32 v[218:219], v[140:141], v[218:219]
	v_pk_mul_f32 v[220:221], v[220:221], v[108:109]
	v_cvt_pk_bf16_f32 v208, v218, v219
	v_cvt_pk_bf16_f32 v190, v220, v221
	v_rcp_f32_e32 v220, v142
	v_rcp_f32_e32 v221, v143
	v_lshlrev_b32_e32 v218, 16, v7
	v_and_b32_e32 v219, 0xffff0000, v7
	v_pk_mul_f32 v[218:219], v[142:143], v[218:219]
	v_pk_mul_f32 v[220:221], v[220:221], v[110:111]
	v_cvt_pk_bf16_f32 v209, v218, v219
	v_cvt_pk_bf16_f32 v191, v220, v221
	v_rcp_f32_e32 v220, v144
	v_rcp_f32_e32 v221, v145
	v_lshlrev_b32_e32 v218, 16, v8
	v_and_b32_e32 v219, 0xffff0000, v8
	v_pk_mul_f32 v[218:219], v[144:145], v[218:219]
	v_pk_mul_f32 v[220:221], v[220:221], v[112:113]
	v_cvt_pk_bf16_f32 v210, v218, v219
	v_cvt_pk_bf16_f32 v192, v220, v221
	v_rcp_f32_e32 v220, v146
	v_rcp_f32_e32 v221, v147
	v_lshlrev_b32_e32 v218, 16, v9
	v_and_b32_e32 v219, 0xffff0000, v9
	v_pk_mul_f32 v[218:219], v[146:147], v[218:219]
	v_pk_mul_f32 v[220:221], v[220:221], v[114:115]
	v_cvt_pk_bf16_f32 v211, v218, v219
	v_cvt_pk_bf16_f32 v193, v220, v221
	v_rcp_f32_e32 v220, v148
	v_rcp_f32_e32 v221, v149
	v_lshlrev_b32_e32 v218, 16, v10
	v_and_b32_e32 v219, 0xffff0000, v10
	v_pk_mul_f32 v[218:219], v[148:149], v[218:219]
	v_pk_mul_f32 v[220:221], v[220:221], v[116:117]
	v_cvt_pk_bf16_f32 v212, v218, v219
	v_cvt_pk_bf16_f32 v194, v220, v221
	v_rcp_f32_e32 v220, v150
	v_rcp_f32_e32 v221, v151
	v_lshlrev_b32_e32 v218, 16, v11
	v_and_b32_e32 v219, 0xffff0000, v11
	v_pk_mul_f32 v[218:219], v[150:151], v[218:219]
	v_pk_mul_f32 v[220:221], v[220:221], v[118:119]
	v_cvt_pk_bf16_f32 v213, v218, v219
	v_cvt_pk_bf16_f32 v195, v220, v221
	v_rcp_f32_e32 v220, v152
	v_rcp_f32_e32 v221, v153
	v_lshlrev_b32_e32 v218, 16, v12
	v_and_b32_e32 v219, 0xffff0000, v12
	v_pk_mul_f32 v[218:219], v[152:153], v[218:219]
	v_pk_mul_f32 v[220:221], v[220:221], v[120:121]
	v_cvt_pk_bf16_f32 v214, v218, v219
	v_cvt_pk_bf16_f32 v196, v220, v221
	v_rcp_f32_e32 v220, v154
	v_rcp_f32_e32 v221, v155
	v_lshlrev_b32_e32 v218, 16, v13
	v_and_b32_e32 v219, 0xffff0000, v13
	v_pk_mul_f32 v[218:219], v[154:155], v[218:219]
	v_pk_mul_f32 v[220:221], v[220:221], v[122:123]
	v_cvt_pk_bf16_f32 v215, v218, v219
	v_cvt_pk_bf16_f32 v197, v220, v221
	v_rcp_f32_e32 v220, v156
	v_rcp_f32_e32 v221, v157
	v_lshlrev_b32_e32 v218, 16, v14
	v_and_b32_e32 v219, 0xffff0000, v14
	v_pk_mul_f32 v[218:219], v[156:157], v[218:219]
	v_pk_mul_f32 v[220:221], v[220:221], v[124:125]
	v_cvt_pk_bf16_f32 v216, v218, v219
	v_cvt_pk_bf16_f32 v198, v220, v221
	v_rcp_f32_e32 v220, v158
	v_rcp_f32_e32 v221, v159
	v_lshlrev_b32_e32 v218, 16, v15
	v_and_b32_e32 v219, 0xffff0000, v15
	v_pk_mul_f32 v[218:219], v[158:159], v[218:219]
	v_pk_mul_f32 v[220:221], v[220:221], v[126:127]
	v_cvt_pk_bf16_f32 v217, v218, v219
	v_cvt_pk_bf16_f32 v199, v220, v221
	ds_write_b128 v222, v[184:187] offset:17408
	ds_write_b128 v223, v[188:191] offset:17408
	ds_write_b128 v224, v[192:195] offset:17408
	ds_write_b128 v225, v[196:199] offset:17408
	ds_write_b128 v227, v[202:205]
	ds_write_b128 v227, v[206:209] offset:16
	ds_write_b128 v227, v[210:213] offset:32
	ds_write_b128 v227, v[214:217] offset:48
	s_waitcnt lgkmcnt(0)
	s_barrier
	s_add_u32 s70, s70, 1
	s_cmp_lt_u32 s70, 32
	s_cbranch_scc1 .Lh2_prep_loop
	s_waitcnt vmcnt(0)
	s_barrier
	s_branch .Lh2_done
.Lh2_mfma:
	s_sub_u32 s1, s0, 4
	v_and_b32_e32 v144, 63, v200
	v_and_b32_e32 v145, 31, v144
	v_lshrrev_b32_e32 v146, 5, v144
	v_bfe_u32 v147, v144, 4, 1
	v_bfe_u32 v148, v144, 2, 2
	v_and_b32_e32 v149, 3, v144
	v_and_b32_e32 v150, 3, v145
	v_bfe_u32 v151, v145, 2, 2
	v_xor_b32_e32 v152, 0, v150
	v_lshlrev_b32_e32 v152, 6, v152
	v_or_b32_e32 v153, 0, v146
	v_xor_b32_e32 v153, v153, v151
	v_lshl_add_u32 v152, v153, 4, v152
	v_lshl_add_u32 v226, v145, 8, v152
	v_xor_b32_e32 v152, 0, v150
	v_lshlrev_b32_e32 v152, 6, v152
	v_or_b32_e32 v153, 2, v146
	v_xor_b32_e32 v153, v153, v151
	v_lshl_add_u32 v152, v153, 4, v152
	v_lshl_add_u32 v227, v145, 8, v152
	v_xor_b32_e32 v152, 1, v150
	v_lshlrev_b32_e32 v152, 6, v152
	v_or_b32_e32 v153, 0, v146
	v_xor_b32_e32 v153, v153, v151
	v_lshl_add_u32 v152, v153, 4, v152
	v_lshl_add_u32 v228, v145, 8, v152
	v_xor_b32_e32 v152, 1, v150
	v_lshlrev_b32_e32 v152, 6, v152
	v_or_b32_e32 v153, 2, v146
	v_xor_b32_e32 v153, v153, v151
	v_lshl_add_u32 v152, v153, 4, v152
	v_lshl_add_u32 v229, v145, 8, v152
	v_xor_b32_e32 v152, 2, v150
	v_lshlrev_b32_e32 v152, 6, v152
	v_or_b32_e32 v153, 0, v146
	v_xor_b32_e32 v153, v153, v151
	v_lshl_add_u32 v152, v153, 4, v152
	v_lshl_add_u32 v230, v145, 8, v152
	v_xor_b32_e32 v152, 2, v150
	v_lshlrev_b32_e32 v152, 6, v152
	v_or_b32_e32 v153, 2, v146
	v_xor_b32_e32 v153, v153, v151
	v_lshl_add_u32 v152, v153, 4, v152
	v_lshl_add_u32 v231, v145, 8, v152
	v_xor_b32_e32 v152, 3, v150
	v_lshlrev_b32_e32 v152, 6, v152
	v_or_b32_e32 v153, 0, v146
	v_xor_b32_e32 v153, v153, v151
	v_lshl_add_u32 v152, v153, 4, v152
	v_lshl_add_u32 v232, v145, 8, v152
	v_xor_b32_e32 v152, 3, v150
	v_lshlrev_b32_e32 v152, 6, v152
	v_or_b32_e32 v153, 2, v146
	v_xor_b32_e32 v153, v153, v151
	v_lshl_add_u32 v152, v153, 4, v152
	v_lshl_add_u32 v233, v145, 8, v152
	v_lshrrev_b32_e32 v154, 1, v149
	v_lshl_or_b32 v154, v147, 1, v154
	v_and_b32_e32 v155, 1, v149
	v_lshlrev_b32_e32 v155, 3, v155
	v_lshlrev_b32_e32 v156, 3, v146
	v_add_u32_e32 v156, 0, v156
	v_add_u32_e32 v156, v156, v148
	v_xor_b32_e32 v157, 0, v148
	v_lshlrev_b32_e32 v157, 6, v157
	v_lshlrev_b32_e32 v158, 1, v146
	v_add_u32_e32 v158, 0, v158
	v_and_b32_e32 v158, 3, v158
	v_xor_b32_e32 v158, v158, v154
	v_lshl_add_u32 v157, v158, 4, v157
	v_add_u32_e32 v157, v157, v155
	v_lshl_add_u32 v234, v156, 8, v157
	v_lshlrev_b32_e32 v156, 3, v146
	v_add_u32_e32 v156, 4, v156
	v_add_u32_e32 v156, v156, v148
	v_xor_b32_e32 v157, 0, v148
	v_lshlrev_b32_e32 v157, 6, v157
	v_lshlrev_b32_e32 v158, 1, v146
	v_add_u32_e32 v158, 1, v158
	v_and_b32_e32 v158, 3, v158
	v_xor_b32_e32 v158, v158, v154
	v_lshl_add_u32 v157, v158, 4, v157
	v_add_u32_e32 v157, v157, v155
	v_lshl_add_u32 v235, v156, 8, v157
	v_lshlrev_b32_e32 v156, 3, v146
	v_add_u32_e32 v156, 0, v156
	v_add_u32_e32 v156, v156, v148
	v_xor_b32_e32 v157, 1, v148
	v_lshlrev_b32_e32 v157, 6, v157
	v_lshlrev_b32_e32 v158, 1, v146
	v_add_u32_e32 v158, 0, v158
	v_and_b32_e32 v158, 3, v158
	v_xor_b32_e32 v158, v158, v154
	v_lshl_add_u32 v157, v158, 4, v157
	v_add_u32_e32 v157, v157, v155
	v_lshl_add_u32 v236, v156, 8, v157
	v_lshlrev_b32_e32 v156, 3, v146
	v_add_u32_e32 v156, 4, v156
	v_add_u32_e32 v156, v156, v148
	v_xor_b32_e32 v157, 1, v148
	v_lshlrev_b32_e32 v157, 6, v157
	v_lshlrev_b32_e32 v158, 1, v146
	v_add_u32_e32 v158, 1, v158
	v_and_b32_e32 v158, 3, v158
	v_xor_b32_e32 v158, v158, v154
	v_lshl_add_u32 v157, v158, 4, v157
	v_add_u32_e32 v157, v157, v155
	v_lshl_add_u32 v237, v156, 8, v157
	v_lshlrev_b32_e32 v156, 3, v146
	v_add_u32_e32 v156, 0, v156
	v_add_u32_e32 v156, v156, v148
	v_xor_b32_e32 v157, 2, v148
	v_lshlrev_b32_e32 v157, 6, v157
	v_lshlrev_b32_e32 v158, 1, v146
	v_add_u32_e32 v158, 0, v158
	v_and_b32_e32 v158, 3, v158
	v_xor_b32_e32 v158, v158, v154
	v_lshl_add_u32 v157, v158, 4, v157
	v_add_u32_e32 v157, v157, v155
	v_lshl_add_u32 v238, v156, 8, v157
	v_lshlrev_b32_e32 v156, 3, v146
	v_add_u32_e32 v156, 4, v156
	v_add_u32_e32 v156, v156, v148
	v_xor_b32_e32 v157, 2, v148
	v_lshlrev_b32_e32 v157, 6, v157
	v_lshlrev_b32_e32 v158, 1, v146
	v_add_u32_e32 v158, 1, v158
	v_and_b32_e32 v158, 3, v158
	v_xor_b32_e32 v158, v158, v154
	v_lshl_add_u32 v157, v158, 4, v157
	v_add_u32_e32 v157, v157, v155
	v_lshl_add_u32 v239, v156, 8, v157
	v_lshlrev_b32_e32 v156, 3, v146
	v_add_u32_e32 v156, 0, v156
	v_add_u32_e32 v156, v156, v148
	v_xor_b32_e32 v157, 3, v148
	v_lshlrev_b32_e32 v157, 6, v157
	v_lshlrev_b32_e32 v158, 1, v146
	v_add_u32_e32 v158, 0, v158
	v_and_b32_e32 v158, 3, v158
	v_xor_b32_e32 v158, v158, v154
	v_lshl_add_u32 v157, v158, 4, v157
	v_add_u32_e32 v157, v157, v155
	v_lshl_add_u32 v240, v156, 8, v157
	v_lshlrev_b32_e32 v156, 3, v146
	v_add_u32_e32 v156, 4, v156
	v_add_u32_e32 v156, v156, v148
	v_xor_b32_e32 v157, 3, v148
	v_lshlrev_b32_e32 v157, 6, v157
	v_lshlrev_b32_e32 v158, 1, v146
	v_add_u32_e32 v158, 1, v158
	v_and_b32_e32 v158, 3, v158
	v_xor_b32_e32 v158, v158, v154
	v_lshl_add_u32 v157, v158, 4, v157
	v_add_u32_e32 v157, v157, v155
	v_lshl_add_u32 v241, v156, 8, v157
	v_lshlrev_b32_e32 v156, 3, v146
	v_add_u32_e32 v156, 0, v156
	v_add_u32_e32 v156, v156, v148
	v_xor_b32_e32 v157, s1, v148
	v_lshlrev_b32_e32 v157, 6, v157
	v_lshlrev_b32_e32 v158, 1, v146
	v_add_u32_e32 v158, 0, v158
	v_and_b32_e32 v158, 3, v158
	v_xor_b32_e32 v158, v158, v154
	v_lshl_add_u32 v157, v158, 4, v157
	v_add_u32_e32 v157, v157, v155
	v_lshl_add_u32 v242, v156, 8, v157
	v_lshlrev_b32_e32 v156, 3, v146
	v_add_u32_e32 v156, 4, v156
	v_add_u32_e32 v156, v156, v148
	v_xor_b32_e32 v157, s1, v148
	v_lshlrev_b32_e32 v157, 6, v157
	v_lshlrev_b32_e32 v158, 1, v146
	v_add_u32_e32 v158, 1, v158
	v_and_b32_e32 v158, 3, v158
	v_xor_b32_e32 v158, v158, v154
	v_lshl_add_u32 v157, v158, 4, v157
	v_add_u32_e32 v157, v157, v155
	v_lshl_add_u32 v243, v156, 8, v157
	v_lshlrev_b32_e32 v156, 2, v146
	v_add_u32_e32 v156, 0, v156
	v_add_u32_e32 v156, v156, v148
	v_xor_b32_e32 v157, s1, v148
	v_lshlrev_b32_e32 v157, 6, v157
	v_add_u32_e32 v158, 0, v146
	v_and_b32_e32 v158, 3, v158
	v_xor_b32_e32 v158, v158, v154
	v_lshl_add_u32 v157, v158, 4, v157
	v_add_u32_e32 v157, v157, v155
	v_lshl_add_u32 v244, v156, 8, v157
	v_lshlrev_b32_e32 v156, 2, v146
	v_add_u32_e32 v156, 8, v156
	v_add_u32_e32 v156, v156, v148
	v_xor_b32_e32 v157, s1, v148
	v_lshlrev_b32_e32 v157, 6, v157
	v_add_u32_e32 v158, 2, v146
	v_and_b32_e32 v158, 3, v158
	v_xor_b32_e32 v158, v158, v154
	v_lshl_add_u32 v157, v158, 4, v157
	v_add_u32_e32 v157, v157, v155
	v_lshl_add_u32 v245, v156, 8, v157
	v_mov_b32_e32 v156, 0x110
	v_add_u32_e32 v157, 0, v145
	v_mul_lo_u32 v157, v157, v156
	v_add_u32_e32 v158, 0x10400, v157
	v_lshl_add_u32 v247, v146, 4, v158
	v_lshl_add_u32 v251, v146, 3, v158
	v_add_u32_e32 v158, 0x14800, v157
	v_lshl_add_u32 v248, v146, 4, v158
	v_lshl_add_u32 v252, v146, 3, v158
	v_add_u32_e32 v157, 32, v145
	v_mul_lo_u32 v157, v157, v156
	v_add_u32_e32 v158, 0x10400, v157
	v_lshl_add_u32 v249, v146, 4, v158
	v_lshl_add_u32 v253, v146, 3, v158
	v_add_u32_e32 v158, 0x14800, v157
	v_lshl_add_u32 v250, v146, 4, v158
	v_lshl_add_u32 v254, v146, 3, v158
	v_lshlrev_b32_e32 v255, 4, v146
	v_lshlrev_b32_e32 v156, 2, v146
	v_add_u32_e32 v157, 0, v156
	v_cmp_gt_u32_e64 s[38:39], v157, v145
	v_add_u32_e32 v157, 1, v156
	v_cmp_gt_u32_e64 s[40:41], v157, v145
	v_add_u32_e32 v157, 2, v156
	v_cmp_gt_u32_e64 s[42:43], v157, v145
	v_add_u32_e32 v157, 3, v156
	v_cmp_gt_u32_e64 s[44:45], v157, v145
	v_add_u32_e32 v157, 8, v156
	v_cmp_gt_u32_e64 s[46:47], v157, v145
	v_add_u32_e32 v157, 9, v156
	v_cmp_gt_u32_e64 s[48:49], v157, v145
	v_add_u32_e32 v157, 10, v156
	v_cmp_gt_u32_e64 s[50:51], v157, v145
	v_add_u32_e32 v157, 11, v156
	v_cmp_gt_u32_e64 s[52:53], v157, v145
	v_add_u32_e32 v157, 16, v156
	v_cmp_gt_u32_e64 s[54:55], v157, v145
	v_add_u32_e32 v157, 17, v156
	v_cmp_gt_u32_e64 s[56:57], v157, v145
	v_add_u32_e32 v157, 18, v156
	v_cmp_gt_u32_e64 s[58:59], v157, v145
	v_add_u32_e32 v157, 19, v156
	v_cmp_gt_u32_e64 s[60:61], v157, v145
	v_add_u32_e32 v157, 24, v156
	v_cmp_gt_u32_e64 s[62:63], v157, v145
	v_add_u32_e32 v157, 25, v156
	v_cmp_gt_u32_e64 s[64:65], v157, v145
	v_add_u32_e32 v157, 26, v156
	v_cmp_gt_u32_e64 s[66:67], v157, v145
	v_add_u32_e32 v157, 27, v156
	v_cmp_gt_u32_e64 s[68:69], v157, v145
	s_mul_i32 s13, s1, 0xa00
	s_add_u32 s13, s13, 0x18c00
	v_mov_b32_e32 v156, 0x50
	v_mul_lo_u32 v157, v145, v156
	v_lshl_add_u32 v157, v146, 3, v157
	v_add_u32_e32 v168, s13, v157
	v_lshrrev_b32_e32 v157, 2, v144
	v_mul_lo_u32 v158, v157, v156
	v_lshl_add_u32 v158, v149, 4, v158
	v_add_u32_e32 v169, s13, v158
	v_add_u32_e32 v170, 0x500, v169
	s_lshl_b32 s13, s8, 12
	v_add_u32_e32 v158, s13, v157
	s_add_u32 s17, s13, 0xfff
	v_sub_u32_e32 v159, s17, v157
	s_cmp_eq_u32 s12, 0
	s_cselect_b64 s[18:19], -1, 0
	v_cndmask_b32_e64 v158, v159, v158, s[18:19]
	v_lshlrev_b32_e32 v158, 10, v158
	v_lshl_add_u32 v171, v149, 4, v158
	s_mov_b32 s33, 0x10000
	s_sub_u32 s13, 0, s33
	s_cmp_eq_u32 s12, 0
	s_cselect_b32 s33, s33, s13
	s_mov_b32 s71, 0
	s_ashr_i32 s72, s33, 2
	s_ashr_i32 s73, s33, 1
	s_add_i32 s75, s73, s72
	s_mov_b32 s13, 0x35000000
	s_cmp_eq_u32 s12, 0
	s_cselect_b32 s13, 0x2d000000, s13
	s_lshl_b32 s17, s9, 8
	s_add_u32 s13, s13, s17
	s_lshl_b32 s17, s1, 6
	s_add_u32 s13, s13, s17
	s_add_u32 s14, s26, s13
	s_addc_u32 s15, s27, 0
	v_mov_b64_e32 v[0:1], 0
	v_mov_b64_e32 v[2:3], 0
	v_mov_b64_e32 v[4:5], 0
	v_mov_b64_e32 v[6:7], 0
	v_mov_b64_e32 v[8:9], 0
	v_mov_b64_e32 v[10:11], 0
	v_mov_b64_e32 v[12:13], 0
	v_mov_b64_e32 v[14:15], 0
	v_mov_b64_e32 v[16:17], 0
	v_mov_b64_e32 v[18:19], 0
	v_mov_b64_e32 v[20:21], 0
	v_mov_b64_e32 v[22:23], 0
	v_mov_b64_e32 v[24:25], 0
	v_mov_b64_e32 v[26:27], 0
	v_mov_b64_e32 v[28:29], 0
	v_mov_b64_e32 v[30:31], 0
	v_mov_b64_e32 v[32:33], 0
	v_mov_b64_e32 v[34:35], 0
	v_mov_b64_e32 v[36:37], 0
	v_mov_b64_e32 v[38:39], 0
	v_mov_b64_e32 v[40:41], 0
	v_mov_b64_e32 v[42:43], 0
	v_mov_b64_e32 v[44:45], 0
	v_mov_b64_e32 v[46:47], 0
	v_mov_b64_e32 v[48:49], 0
	v_mov_b64_e32 v[50:51], 0
	v_mov_b64_e32 v[52:53], 0
	v_mov_b64_e32 v[54:55], 0
	v_mov_b64_e32 v[56:57], 0
	v_mov_b64_e32 v[58:59], 0
	v_mov_b64_e32 v[60:61], 0
	v_mov_b64_e32 v[62:63], 0
	v_add_u32_e32 v244, 0x8400, v244
	v_add_u32_e32 v245, 0x8400, v245
	v_add_u32_e32 v242, 0x8400, v242
	v_add_u32_e32 v243, 0x8400, v243
	s_mov_b32 s76, 0x8400
	s_mov_b32 s70, 0
	s_barrier
.Lh2_mfma_loop:
	ds_read_b128 v[64:67], v247
	ds_read_b128 v[144:147], v226 offset:1024
	ds_read_b128 v[68:71], v247 offset:32
	ds_read_b128 v[148:151], v227 offset:1024
	ds_read_b128 v[72:75], v247 offset:64
	ds_read_b128 v[152:155], v228 offset:1024
	ds_read_b128 v[76:79], v247 offset:96
	ds_read_b128 v[156:159], v229 offset:1024
	ds_read_b128 v[80:83], v247 offset:128
	ds_read_b128 v[184:187], v230 offset:1024
	ds_read_b128 v[84:87], v247 offset:160
	ds_read_b128 v[188:191], v231 offset:1024
	s_waitcnt lgkmcnt(10)
	v_mfma_f32_32x32x16_bf16 v[96:111], v[144:147], v[64:67], 0
	ds_read_b128 v[88:91], v247 offset:192
	ds_read_b128 v[192:195], v232 offset:1024
	s_waitcnt lgkmcnt(10)
	v_mfma_f32_32x32x16_bf16 v[96:111], v[148:151], v[68:71], v[96:111]
	ds_read_b128 v[92:95], v247 offset:224
	ds_read_b128 v[196:199], v233 offset:1024
	s_waitcnt lgkmcnt(10)
	v_mfma_f32_32x32x16_bf16 v[96:111], v[152:155], v[72:75], v[96:111]
	ds_read_b64_tr_b16 v[202:203], v244 offset:0
	ds_read_b64_tr_b16 v[204:205], v245 offset:0
	s_waitcnt lgkmcnt(10)
	v_mfma_f32_32x32x16_bf16 v[96:111], v[156:159], v[76:79], v[96:111]
	ds_read_b64_tr_b16 v[206:207], v244 offset:4096
	ds_read_b64_tr_b16 v[208:209], v245 offset:4096
	s_waitcnt lgkmcnt(10)
	v_mfma_f32_32x32x16_bf16 v[96:111], v[184:187], v[80:83], v[96:111]
	ds_read2_b64 v[210:213], v251 offset0:0 offset1:2
	ds_read2_b64 v[214:217], v251 offset0:4 offset1:6
	s_waitcnt lgkmcnt(10)
	v_mfma_f32_32x32x16_bf16 v[96:111], v[188:191], v[84:87], v[96:111]
	ds_read2_b64 v[144:147], v251 offset0:8 offset1:10
	ds_read2_b64 v[148:151], v251 offset0:12 offset1:14
	s_waitcnt lgkmcnt(10)
	v_mfma_f32_32x32x16_bf16 v[96:111], v[192:195], v[88:91], v[96:111]
	ds_read2_b64 v[152:155], v251 offset0:16 offset1:18
	ds_read2_b64 v[156:159], v251 offset0:20 offset1:22
	s_waitcnt lgkmcnt(10)
	v_mfma_f32_32x32x16_bf16 v[96:111], v[196:199], v[92:95], v[96:111]
	ds_read2_b64 v[184:187], v251 offset0:24 offset1:26
	ds_read2_b64 v[188:191], v251 offset0:28 offset1:30
	s_waitcnt lgkmcnt(10)
	s_nop 8
	v_cndmask_b32_e64 v96, v96, 0, s[38:39]
	v_cndmask_b32_e64 v97, v97, 0, s[40:41]
	v_cndmask_b32_e64 v98, v98, 0, s[42:43]
	v_cndmask_b32_e64 v99, v99, 0, s[44:45]
	v_cndmask_b32_e64 v100, v100, 0, s[46:47]
	v_cndmask_b32_e64 v101, v101, 0, s[48:49]
	v_cndmask_b32_e64 v102, v102, 0, s[50:51]
	v_cndmask_b32_e64 v103, v103, 0, s[52:53]
	v_cndmask_b32_e64 v104, v104, 0, s[54:55]
	v_cndmask_b32_e64 v105, v105, 0, s[56:57]
	v_cndmask_b32_e64 v106, v106, 0, s[58:59]
	v_cndmask_b32_e64 v107, v107, 0, s[60:61]
	v_cndmask_b32_e64 v108, v108, 0, s[62:63]
	v_cndmask_b32_e64 v109, v109, 0, s[64:65]
	v_cndmask_b32_e64 v110, v110, 0, s[66:67]
	v_cndmask_b32_e64 v111, v111, 0, s[68:69]
	v_cvt_pk_bf16_f32 v96, v96, v97
	v_cvt_pk_bf16_f32 v97, v98, v99
	v_cvt_pk_bf16_f32 v98, v100, v101
	v_cvt_pk_bf16_f32 v99, v102, v103
	v_cvt_pk_bf16_f32 v100, v104, v105
	v_cvt_pk_bf16_f32 v101, v106, v107
	v_cvt_pk_bf16_f32 v102, v108, v109
	v_cvt_pk_bf16_f32 v103, v110, v111
	v_mfma_f32_32x32x16_bf16 v[128:143], v[202:205], v[96:99], 0
	s_waitcnt lgkmcnt(8)
	v_mfma_f32_32x32x16_bf16 v[128:143], v[206:209], v[100:103], v[128:143]
	v_cvt_pk_bf16_f32 v218, v0, v1
	v_cvt_pk_bf16_f32 v219, v2, v3
	v_cvt_pk_bf16_f32 v220, v4, v5
	v_cvt_pk_bf16_f32 v221, v6, v7
	s_waitcnt lgkmcnt(7)
	s_nop 1
	v_mfma_f32_32x32x16_bf16 v[128:143], v[218:221], v[210:213], v[128:143]
	v_cvt_pk_bf16_f32 v222, v8, v9
	v_cvt_pk_bf16_f32 v223, v10, v11
	v_cvt_pk_bf16_f32 v224, v12, v13
	v_cvt_pk_bf16_f32 v225, v14, v15
	s_waitcnt lgkmcnt(6)
	s_nop 1
	v_mfma_f32_32x32x16_bf16 v[128:143], v[222:225], v[214:217], v[128:143]
	v_cvt_pk_bf16_f32 v218, v16, v17
	v_cvt_pk_bf16_f32 v219, v18, v19
	v_cvt_pk_bf16_f32 v220, v20, v21
	v_cvt_pk_bf16_f32 v221, v22, v23
	s_waitcnt lgkmcnt(5)
	s_nop 1
	v_mfma_f32_32x32x16_bf16 v[128:143], v[218:221], v[144:147], v[128:143]
	v_cvt_pk_bf16_f32 v222, v24, v25
	v_cvt_pk_bf16_f32 v223, v26, v27
	v_cvt_pk_bf16_f32 v224, v28, v29
	v_cvt_pk_bf16_f32 v225, v30, v31
	s_waitcnt lgkmcnt(4)
	s_nop 1
	v_mfma_f32_32x32x16_bf16 v[128:143], v[222:225], v[148:151], v[128:143]
	v_cvt_pk_bf16_f32 v218, v32, v33
	v_cvt_pk_bf16_f32 v219, v34, v35
	v_cvt_pk_bf16_f32 v220, v36, v37
	v_cvt_pk_bf16_f32 v221, v38, v39
	s_waitcnt lgkmcnt(3)
	s_nop 1
	v_mfma_f32_32x32x16_bf16 v[128:143], v[218:221], v[152:155], v[128:143]
	v_cvt_pk_bf16_f32 v222, v40, v41
	v_cvt_pk_bf16_f32 v223, v42, v43
	v_cvt_pk_bf16_f32 v224, v44, v45
	v_cvt_pk_bf16_f32 v225, v46, v47
	s_waitcnt lgkmcnt(2)
	s_nop 1
	v_mfma_f32_32x32x16_bf16 v[128:143], v[222:225], v[156:159], v[128:143]
	v_cvt_pk_bf16_f32 v218, v48, v49
	v_cvt_pk_bf16_f32 v219, v50, v51
	v_cvt_pk_bf16_f32 v220, v52, v53
	v_cvt_pk_bf16_f32 v221, v54, v55
	s_waitcnt lgkmcnt(1)
	s_nop 1
	v_mfma_f32_32x32x16_bf16 v[128:143], v[218:221], v[184:187], v[128:143]
	v_cvt_pk_bf16_f32 v222, v56, v57
	v_cvt_pk_bf16_f32 v223, v58, v59
	v_cvt_pk_bf16_f32 v224, v60, v61
	v_cvt_pk_bf16_f32 v225, v62, v63
	s_waitcnt lgkmcnt(0)
	s_nop 1
	v_mfma_f32_32x32x16_bf16 v[128:143], v[222:225], v[188:191], v[128:143]
	ds_read_b128 v[64:67], v249
	ds_read_b128 v[192:195], v226 offset:1024
	ds_read_b128 v[68:71], v249 offset:32
	ds_read_b128 v[196:199], v227 offset:1024
	ds_read_b128 v[72:75], v249 offset:64
	ds_read_b128 v[202:205], v228 offset:1024
	ds_read_b128 v[76:79], v249 offset:96
	ds_read_b128 v[206:209], v229 offset:1024
	ds_read_b128 v[80:83], v249 offset:128
	ds_read_b128 v[210:213], v230 offset:1024
	ds_read_b128 v[84:87], v249 offset:160
	ds_read_b128 v[214:217], v231 offset:1024
	s_waitcnt lgkmcnt(11)
	v_cvt_pk_bf16_f32 v218, v128, v129
	v_cvt_pk_bf16_f32 v219, v130, v131
	v_cvt_pk_bf16_f32 v220, v132, v133
	v_cvt_pk_bf16_f32 v221, v134, v135
	v_cvt_pk_bf16_f32 v222, v136, v137
	v_cvt_pk_bf16_f32 v223, v138, v139
	v_cvt_pk_bf16_f32 v224, v140, v141
	v_cvt_pk_bf16_f32 v225, v142, v143
	ds_write2_b64 v168, v[218:219], v[220:221] offset1:2
	ds_write2_b64 v168, v[222:223], v[224:225] offset0:4 offset1:6
	ds_read_b128 v[218:221], v169
	ds_read_b128 v[222:225], v170
	v_add_u32_e32 v183, s71, v171
	v_add_u32_e32 v201, s72, v171
	s_waitcnt lgkmcnt(0)
	global_store_dwordx4 v183, v[218:221], s[14:15]
	global_store_dwordx4 v201, v[222:225], s[14:15]
	ds_read_b128 v[88:91], v249 offset:192
	ds_read_b128 v[144:147], v232 offset:1024
	ds_read_b128 v[92:95], v249 offset:224
	ds_read_b128 v[148:151], v233 offset:1024
	ds_read_b128 v[152:155], v226 offset:9216
	ds_read_b128 v[156:159], v227 offset:9216
	ds_read_b128 v[184:187], v228 offset:9216
	ds_read_b128 v[188:191], v229 offset:9216
	v_mfma_f32_32x32x16_bf16 v[96:111], v[192:195], v[64:67], 0
	ds_read_b128 v[192:195], v230 offset:9216
	v_mfma_f32_32x32x16_bf16 v[96:111], v[196:199], v[68:71], v[96:111]
	ds_read_b128 v[196:199], v231 offset:9216
	v_mfma_f32_32x32x16_bf16 v[96:111], v[202:205], v[72:75], v[96:111]
	ds_read_b128 v[202:205], v232 offset:9216
	v_mfma_f32_32x32x16_bf16 v[96:111], v[206:209], v[76:79], v[96:111]
	ds_read_b128 v[206:209], v233 offset:9216
	v_mfma_f32_32x32x16_bf16 v[96:111], v[210:213], v[80:83], v[96:111]
	v_mfma_f32_32x32x16_bf16 v[96:111], v[214:217], v[84:87], v[96:111]
	s_waitcnt lgkmcnt(10)
	v_mfma_f32_32x32x16_bf16 v[96:111], v[144:147], v[88:91], v[96:111]
	ds_read_b64_tr_b16 v[210:211], v244 offset:0
	ds_read_b64_tr_b16 v[212:213], v245 offset:0
	s_waitcnt lgkmcnt(10)
	v_mfma_f32_32x32x16_bf16 v[96:111], v[148:151], v[92:95], v[96:111]
	ds_read_b64_tr_b16 v[214:215], v244 offset:4096
	ds_read_b64_tr_b16 v[216:217], v245 offset:4096
	s_waitcnt lgkmcnt(11)
	v_mfma_f32_32x32x16_bf16 v[112:127], v[152:155], v[64:67], 0
	s_waitcnt lgkmcnt(10)
	v_mfma_f32_32x32x16_bf16 v[112:127], v[156:159], v[68:71], v[112:127]
	ds_read_b64_tr_b16 v[144:145], v244 offset:8192
	ds_read_b64_tr_b16 v[146:147], v245 offset:8192
	s_waitcnt lgkmcnt(11)
	v_mfma_f32_32x32x16_bf16 v[112:127], v[184:187], v[72:75], v[112:127]
	s_waitcnt lgkmcnt(10)
	v_mfma_f32_32x32x16_bf16 v[112:127], v[188:191], v[76:79], v[112:127]
	ds_read_b64_tr_b16 v[148:149], v244 offset:12288
	ds_read_b64_tr_b16 v[150:151], v245 offset:12288
	s_waitcnt lgkmcnt(11)
	v_mfma_f32_32x32x16_bf16 v[112:127], v[192:195], v[80:83], v[112:127]
	ds_read2_b64 v[152:155], v253 offset0:0 offset1:2
	s_waitcnt lgkmcnt(11)
	v_mfma_f32_32x32x16_bf16 v[112:127], v[196:199], v[84:87], v[112:127]
	ds_read2_b64 v[156:159], v253 offset0:4 offset1:6
	s_waitcnt lgkmcnt(11)
	v_mfma_f32_32x32x16_bf16 v[112:127], v[202:205], v[88:91], v[112:127]
	ds_read2_b64 v[184:187], v253 offset0:8 offset1:10
	s_waitcnt lgkmcnt(11)
	v_mfma_f32_32x32x16_bf16 v[112:127], v[206:209], v[92:95], v[112:127]
	ds_read2_b64 v[188:191], v253 offset0:12 offset1:14
	s_waitcnt lgkmcnt(10)
	v_cvt_pk_bf16_f32 v96, v96, v97
	v_cvt_pk_bf16_f32 v97, v98, v99
	v_cvt_pk_bf16_f32 v98, v100, v101
	v_cvt_pk_bf16_f32 v99, v102, v103
	v_cvt_pk_bf16_f32 v100, v104, v105
	v_cvt_pk_bf16_f32 v101, v106, v107
	v_cvt_pk_bf16_f32 v102, v108, v109
	v_cvt_pk_bf16_f32 v103, v110, v111
	s_nop 1
	v_cndmask_b32_e64 v112, v112, 0, s[38:39]
	v_cndmask_b32_e64 v113, v113, 0, s[40:41]
	v_cndmask_b32_e64 v114, v114, 0, s[42:43]
	v_cndmask_b32_e64 v115, v115, 0, s[44:45]
	v_cndmask_b32_e64 v116, v116, 0, s[46:47]
	v_cndmask_b32_e64 v117, v117, 0, s[48:49]
	v_cndmask_b32_e64 v118, v118, 0, s[50:51]
	v_cndmask_b32_e64 v119, v119, 0, s[52:53]
	v_cndmask_b32_e64 v120, v120, 0, s[54:55]
	v_cndmask_b32_e64 v121, v121, 0, s[56:57]
	v_cndmask_b32_e64 v122, v122, 0, s[58:59]
	v_cndmask_b32_e64 v123, v123, 0, s[60:61]
	v_cndmask_b32_e64 v124, v124, 0, s[62:63]
	v_cndmask_b32_e64 v125, v125, 0, s[64:65]
	v_cndmask_b32_e64 v126, v126, 0, s[66:67]
	v_cndmask_b32_e64 v127, v127, 0, s[68:69]
	v_cvt_pk_bf16_f32 v112, v112, v113
	v_cvt_pk_bf16_f32 v113, v114, v115
	v_cvt_pk_bf16_f32 v114, v116, v117
	v_cvt_pk_bf16_f32 v115, v118, v119
	v_cvt_pk_bf16_f32 v116, v120, v121
	v_cvt_pk_bf16_f32 v117, v122, v123
	v_cvt_pk_bf16_f32 v118, v124, v125
	v_cvt_pk_bf16_f32 v119, v126, v127
	ds_read2_b64 v[192:195], v253 offset0:16 offset1:18
	ds_read2_b64 v[196:199], v253 offset0:20 offset1:22
	v_mfma_f32_32x32x16_bf16 v[128:143], v[210:213], v[96:99], 0
	s_waitcnt lgkmcnt(10)
	v_mfma_f32_32x32x16_bf16 v[128:143], v[214:217], v[100:103], v[128:143]
	ds_read2_b64 v[202:205], v253 offset0:24 offset1:26
	ds_read2_b64 v[206:209], v253 offset0:28 offset1:30
	s_waitcnt lgkmcnt(10)
	v_mfma_f32_32x32x16_bf16 v[128:143], v[144:147], v[112:115], v[128:143]
	ds_read_b64_tr_b16 v[210:211], v242 offset:0
	ds_read_b64_tr_b16 v[212:213], v243 offset:0
	s_waitcnt lgkmcnt(10)
	v_mfma_f32_32x32x16_bf16 v[128:143], v[148:151], v[116:119], v[128:143]
	v_cvt_pk_bf16_f32 v218, v0, v1
	v_cvt_pk_bf16_f32 v219, v2, v3
	v_cvt_pk_bf16_f32 v220, v4, v5
	v_cvt_pk_bf16_f32 v221, v6, v7
	ds_read_b64_tr_b16 v[214:215], v234 offset:1024
	ds_read_b64_tr_b16 v[216:217], v235 offset:1024
	s_waitcnt lgkmcnt(11)
	s_nop 1
	v_mfma_f32_32x32x16_bf16 v[128:143], v[218:221], v[152:155], v[128:143]
	v_cvt_pk_bf16_f32 v222, v8, v9
	v_cvt_pk_bf16_f32 v223, v10, v11
	v_cvt_pk_bf16_f32 v224, v12, v13
	v_cvt_pk_bf16_f32 v225, v14, v15
	s_waitcnt lgkmcnt(10)
	s_nop 1
	v_mfma_f32_32x32x16_bf16 v[128:143], v[222:225], v[156:159], v[128:143]
	v_cvt_pk_bf16_f32 v218, v16, v17
	v_cvt_pk_bf16_f32 v219, v18, v19
	v_cvt_pk_bf16_f32 v220, v20, v21
	v_cvt_pk_bf16_f32 v221, v22, v23
	ds_read_b64_tr_b16 v[144:145], v236 offset:1024
	ds_read_b64_tr_b16 v[146:147], v237 offset:1024
	s_waitcnt lgkmcnt(11)
	s_nop 1
	v_mfma_f32_32x32x16_bf16 v[128:143], v[218:221], v[184:187], v[128:143]
	v_cvt_pk_bf16_f32 v222, v24, v25
	v_cvt_pk_bf16_f32 v223, v26, v27
	v_cvt_pk_bf16_f32 v224, v28, v29
	v_cvt_pk_bf16_f32 v225, v30, v31
	s_waitcnt lgkmcnt(10)
	s_nop 1
	v_mfma_f32_32x32x16_bf16 v[128:143], v[222:225], v[188:191], v[128:143]
	v_cvt_pk_bf16_f32 v218, v32, v33
	v_cvt_pk_bf16_f32 v219, v34, v35
	v_cvt_pk_bf16_f32 v220, v36, v37
	v_cvt_pk_bf16_f32 v221, v38, v39
	ds_read_b64_tr_b16 v[148:149], v238 offset:1024
	ds_read_b64_tr_b16 v[150:151], v239 offset:1024
	s_waitcnt lgkmcnt(11)
	s_nop 1
	v_mfma_f32_32x32x16_bf16 v[128:143], v[218:221], v[192:195], v[128:143]
	v_cvt_pk_bf16_f32 v222, v40, v41
	v_cvt_pk_bf16_f32 v223, v42, v43
	v_cvt_pk_bf16_f32 v224, v44, v45
	v_cvt_pk_bf16_f32 v225, v46, v47
	s_waitcnt lgkmcnt(10)
	s_nop 1
	v_mfma_f32_32x32x16_bf16 v[128:143], v[222:225], v[196:199], v[128:143]
	v_cvt_pk_bf16_f32 v218, v48, v49
	v_cvt_pk_bf16_f32 v219, v50, v51
	v_cvt_pk_bf16_f32 v220, v52, v53
	v_cvt_pk_bf16_f32 v221, v54, v55
	ds_read_b64_tr_b16 v[152:153], v240 offset:1024
	ds_read_b64_tr_b16 v[154:155], v241 offset:1024
	s_waitcnt lgkmcnt(11)
	s_nop 1
	v_mfma_f32_32x32x16_bf16 v[128:143], v[218:221], v[202:205], v[128:143]
	v_cvt_pk_bf16_f32 v222, v56, v57
	v_cvt_pk_bf16_f32 v223, v58, v59
	v_cvt_pk_bf16_f32 v224, v60, v61
	v_cvt_pk_bf16_f32 v225, v62, v63
	s_waitcnt lgkmcnt(10)
	s_nop 1
	v_mfma_f32_32x32x16_bf16 v[128:143], v[222:225], v[206:209], v[128:143]
	ds_read_b64_tr_b16 v[156:157], v242 offset:4096
	ds_read_b64_tr_b16 v[158:159], v243 offset:4096
	s_waitcnt lgkmcnt(10)
	s_nop 8
	v_cvt_pk_bf16_f32 v218, v128, v129
	v_cvt_pk_bf16_f32 v219, v130, v131
	v_cvt_pk_bf16_f32 v220, v132, v133
	v_cvt_pk_bf16_f32 v221, v134, v135
	v_cvt_pk_bf16_f32 v222, v136, v137
	v_cvt_pk_bf16_f32 v223, v138, v139
	v_cvt_pk_bf16_f32 v224, v140, v141
	v_cvt_pk_bf16_f32 v225, v142, v143
	ds_write2_b64 v168, v[218:219], v[220:221] offset1:2
	ds_write2_b64 v168, v[222:223], v[224:225] offset0:4 offset1:6
	ds_read_b128 v[218:221], v169
	ds_read_b128 v[222:225], v170
	v_add_u32_e32 v183, s73, v171
	v_add_u32_e32 v201, s75, v171
	s_waitcnt lgkmcnt(0)
	global_store_dwordx4 v183, v[218:221], s[14:15]
	global_store_dwordx4 v201, v[222:225], s[14:15]
	ds_read_b64_tr_b16 v[184:185], v234 offset:5120
	ds_read_b64_tr_b16 v[186:187], v235 offset:5120
	ds_read_b64_tr_b16 v[188:189], v236 offset:5120
	ds_read_b64_tr_b16 v[190:191], v237 offset:5120
	ds_read_b64_tr_b16 v[192:193], v238 offset:5120
	ds_read_b64_tr_b16 v[194:195], v239 offset:5120
	ds_read_b64_tr_b16 v[196:197], v240 offset:5120
	ds_read_b64_tr_b16 v[198:199], v241 offset:5120
	ds_read_b64_tr_b16 v[202:203], v242 offset:8192
	ds_read_b64_tr_b16 v[204:205], v243 offset:8192
	ds_read_b64_tr_b16 v[206:207], v234 offset:9216
	ds_read_b64_tr_b16 v[208:209], v235 offset:9216
	v_mfma_f32_32x32x16_bf16 v[0:15], v[214:217], v[210:213], v[0:15]
	v_mfma_f32_32x32x16_bf16 v[16:31], v[144:147], v[210:213], v[16:31]
	v_mfma_f32_32x32x16_bf16 v[32:47], v[148:151], v[210:213], v[32:47]
	v_mfma_f32_32x32x16_bf16 v[48:63], v[152:155], v[210:213], v[48:63]
	s_waitcnt lgkmcnt(10)
	v_mfma_f32_32x32x16_bf16 v[0:15], v[184:187], v[156:159], v[0:15]
	ds_read_b64_tr_b16 v[214:215], v236 offset:9216
	ds_read_b64_tr_b16 v[216:217], v237 offset:9216
	s_waitcnt lgkmcnt(10)
	v_mfma_f32_32x32x16_bf16 v[16:31], v[188:191], v[156:159], v[16:31]
	ds_read_b64_tr_b16 v[144:145], v238 offset:9216
	ds_read_b64_tr_b16 v[146:147], v239 offset:9216
	s_waitcnt lgkmcnt(10)
	v_mfma_f32_32x32x16_bf16 v[32:47], v[192:195], v[156:159], v[32:47]
	ds_read_b64_tr_b16 v[148:149], v240 offset:9216
	ds_read_b64_tr_b16 v[150:151], v241 offset:9216
	s_waitcnt lgkmcnt(10)
	v_mfma_f32_32x32x16_bf16 v[48:63], v[196:199], v[156:159], v[48:63]
	ds_read_b64_tr_b16 v[152:153], v242 offset:12288
	ds_read_b64_tr_b16 v[154:155], v243 offset:12288
	s_waitcnt lgkmcnt(8)
	v_mfma_f32_32x32x16_bf16 v[0:15], v[206:209], v[202:205], v[0:15]
	ds_read_b64_tr_b16 v[210:211], v234 offset:13312
	ds_read_b64_tr_b16 v[212:213], v235 offset:13312
	ds_read_b64_tr_b16 v[184:185], v236 offset:13312
	ds_read_b64_tr_b16 v[186:187], v237 offset:13312
	s_waitcnt lgkmcnt(10)
	v_mfma_f32_32x32x16_bf16 v[16:31], v[214:217], v[202:205], v[16:31]
	ds_read_b64_tr_b16 v[188:189], v238 offset:13312
	ds_read_b64_tr_b16 v[190:191], v239 offset:13312
	s_waitcnt lgkmcnt(10)
	v_mfma_f32_32x32x16_bf16 v[32:47], v[144:147], v[202:205], v[32:47]
	ds_read_b64_tr_b16 v[192:193], v240 offset:13312
	ds_read_b64_tr_b16 v[194:195], v241 offset:13312
	s_waitcnt lgkmcnt(10)
	v_mfma_f32_32x32x16_bf16 v[48:63], v[148:151], v[202:205], v[48:63]
	ds_read_b128 v[196:199], v255 offset:0
	ds_read_b128 v[156:159], v255 offset:32
	s_waitcnt lgkmcnt(8)
	v_mfma_f32_32x32x16_bf16 v[0:15], v[210:213], v[152:155], v[0:15]
	ds_read_b128 v[206:209], v255 offset:64
	ds_read_b128 v[214:217], v255 offset:96
	ds_read_b128 v[144:147], v255 offset:128
	ds_read_b128 v[148:151], v255 offset:160
	s_waitcnt lgkmcnt(10)
	v_mfma_f32_32x32x16_bf16 v[16:31], v[184:187], v[152:155], v[16:31]
	ds_read_b128 v[202:205], v255 offset:192
	ds_read_b128 v[210:213], v255 offset:224
	s_waitcnt lgkmcnt(10)
	v_mfma_f32_32x32x16_bf16 v[32:47], v[188:191], v[152:155], v[32:47]
	ds_read_b128 v[184:187], v255 offset:256
	ds_read_b128 v[188:191], v255 offset:288
	s_waitcnt lgkmcnt(10)
	v_mfma_f32_32x32x16_bf16 v[48:63], v[192:195], v[152:155], v[48:63]
	ds_read_b128 v[192:195], v255 offset:320
	ds_read_b128 v[152:155], v255 offset:352
	s_waitcnt lgkmcnt(11)
	v_pk_mul_f32 v[0:1], v[0:1], v[196:197]
	v_pk_mul_f32 v[2:3], v[2:3], v[198:199]
	ds_read_b128 v[196:199], v255 offset:384
	s_waitcnt lgkmcnt(11)
	v_pk_mul_f32 v[4:5], v[4:5], v[156:157]
	v_pk_mul_f32 v[6:7], v[6:7], v[158:159]
	ds_read_b128 v[156:159], v255 offset:416
	s_waitcnt lgkmcnt(11)
	v_pk_mul_f32 v[8:9], v[8:9], v[206:207]
	v_pk_mul_f32 v[10:11], v[10:11], v[208:209]
	ds_read_b128 v[206:209], v255 offset:448
	s_waitcnt lgkmcnt(11)
	v_pk_mul_f32 v[12:13], v[12:13], v[214:215]
	v_pk_mul_f32 v[14:15], v[14:15], v[216:217]
	ds_read_b128 v[214:217], v255 offset:480
	s_waitcnt lgkmcnt(11)
	v_pk_mul_f32 v[16:17], v[16:17], v[144:145]
	v_pk_mul_f32 v[18:19], v[18:19], v[146:147]
	s_waitcnt lgkmcnt(10)
	v_pk_mul_f32 v[20:21], v[20:21], v[148:149]
	v_pk_mul_f32 v[22:23], v[22:23], v[150:151]
	s_waitcnt lgkmcnt(9)
	v_pk_mul_f32 v[24:25], v[24:25], v[202:203]
	v_pk_mul_f32 v[26:27], v[26:27], v[204:205]
	s_waitcnt lgkmcnt(8)
	v_pk_mul_f32 v[28:29], v[28:29], v[210:211]
	v_pk_mul_f32 v[30:31], v[30:31], v[212:213]
	s_waitcnt lgkmcnt(7)
	v_pk_mul_f32 v[32:33], v[32:33], v[184:185]
	v_pk_mul_f32 v[34:35], v[34:35], v[186:187]
	s_waitcnt lgkmcnt(6)
	v_pk_mul_f32 v[36:37], v[36:37], v[188:189]
	v_pk_mul_f32 v[38:39], v[38:39], v[190:191]
	s_waitcnt lgkmcnt(5)
	v_pk_mul_f32 v[40:41], v[40:41], v[192:193]
	v_pk_mul_f32 v[42:43], v[42:43], v[194:195]
	s_waitcnt lgkmcnt(4)
	v_pk_mul_f32 v[44:45], v[44:45], v[152:153]
	v_pk_mul_f32 v[46:47], v[46:47], v[154:155]
	s_waitcnt lgkmcnt(3)
	v_pk_mul_f32 v[48:49], v[48:49], v[196:197]
	v_pk_mul_f32 v[50:51], v[50:51], v[198:199]
	s_waitcnt lgkmcnt(2)
	v_pk_mul_f32 v[52:53], v[52:53], v[156:157]
	v_pk_mul_f32 v[54:55], v[54:55], v[158:159]
	s_waitcnt lgkmcnt(1)
	v_pk_mul_f32 v[56:57], v[56:57], v[206:207]
	v_pk_mul_f32 v[58:59], v[58:59], v[208:209]
	s_waitcnt lgkmcnt(0)
	v_pk_mul_f32 v[60:61], v[60:61], v[214:215]
	v_pk_mul_f32 v[62:63], v[62:63], v[216:217]
	v_add_u32_e32 v171, s33, v171
	s_mov_b32 s77, s76
	s_add_u32 s76, s76, 0x4000
	s_cmp_eq_u32 s76, 0x10400
	s_cselect_b32 s76, 0x24000, s76
	s_cmp_eq_u32 s76, 0x28000
	s_cselect_b32 s76, 0x8400, s76
	s_sub_u32 s77, s76, s77
	v_add_u32_e32 v244, s77, v244
	v_add_u32_e32 v245, s77, v245
	v_add_u32_e32 v242, s77, v242
	v_add_u32_e32 v243, s77, v243
	s_barrier
	ds_read_b128 v[64:67], v248
	ds_read_b128 v[144:147], v226 offset:17408
	ds_read_b128 v[68:71], v248 offset:32
	ds_read_b128 v[148:151], v227 offset:17408
	ds_read_b128 v[72:75], v248 offset:64
	ds_read_b128 v[152:155], v228 offset:17408
	ds_read_b128 v[76:79], v248 offset:96
	ds_read_b128 v[156:159], v229 offset:17408
	ds_read_b128 v[80:83], v248 offset:128
	ds_read_b128 v[184:187], v230 offset:17408
	ds_read_b128 v[84:87], v248 offset:160
	ds_read_b128 v[188:191], v231 offset:17408
	s_waitcnt lgkmcnt(10)
	v_mfma_f32_32x32x16_bf16 v[96:111], v[144:147], v[64:67], 0
	ds_read_b128 v[88:91], v248 offset:192
	ds_read_b128 v[192:195], v232 offset:17408
	s_waitcnt lgkmcnt(10)
	v_mfma_f32_32x32x16_bf16 v[96:111], v[148:151], v[68:71], v[96:111]
	ds_read_b128 v[92:95], v248 offset:224
	ds_read_b128 v[196:199], v233 offset:17408
	s_waitcnt lgkmcnt(10)
	v_mfma_f32_32x32x16_bf16 v[96:111], v[152:155], v[72:75], v[96:111]
	ds_read_b64_tr_b16 v[202:203], v244 offset:0
	ds_read_b64_tr_b16 v[204:205], v245 offset:0
	s_waitcnt lgkmcnt(10)
	v_mfma_f32_32x32x16_bf16 v[96:111], v[156:159], v[76:79], v[96:111]
	ds_read_b64_tr_b16 v[206:207], v244 offset:4096
	ds_read_b64_tr_b16 v[208:209], v245 offset:4096
	s_waitcnt lgkmcnt(10)
	v_mfma_f32_32x32x16_bf16 v[96:111], v[184:187], v[80:83], v[96:111]
	ds_read2_b64 v[210:213], v252 offset0:0 offset1:2
	ds_read2_b64 v[214:217], v252 offset0:4 offset1:6
	s_waitcnt lgkmcnt(10)
	v_mfma_f32_32x32x16_bf16 v[96:111], v[188:191], v[84:87], v[96:111]
	ds_read2_b64 v[144:147], v252 offset0:8 offset1:10
	ds_read2_b64 v[148:151], v252 offset0:12 offset1:14
	s_waitcnt lgkmcnt(10)
	v_mfma_f32_32x32x16_bf16 v[96:111], v[192:195], v[88:91], v[96:111]
	ds_read2_b64 v[152:155], v252 offset0:16 offset1:18
	ds_read2_b64 v[156:159], v252 offset0:20 offset1:22
	s_waitcnt lgkmcnt(10)
	v_mfma_f32_32x32x16_bf16 v[96:111], v[196:199], v[92:95], v[96:111]
	ds_read2_b64 v[184:187], v252 offset0:24 offset1:26
	ds_read2_b64 v[188:191], v252 offset0:28 offset1:30
	s_waitcnt lgkmcnt(10)
	s_nop 8
	v_cndmask_b32_e64 v96, v96, 0, s[38:39]
	v_cndmask_b32_e64 v97, v97, 0, s[40:41]
	v_cndmask_b32_e64 v98, v98, 0, s[42:43]
	v_cndmask_b32_e64 v99, v99, 0, s[44:45]
	v_cndmask_b32_e64 v100, v100, 0, s[46:47]
	v_cndmask_b32_e64 v101, v101, 0, s[48:49]
	v_cndmask_b32_e64 v102, v102, 0, s[50:51]
	v_cndmask_b32_e64 v103, v103, 0, s[52:53]
	v_cndmask_b32_e64 v104, v104, 0, s[54:55]
	v_cndmask_b32_e64 v105, v105, 0, s[56:57]
	v_cndmask_b32_e64 v106, v106, 0, s[58:59]
	v_cndmask_b32_e64 v107, v107, 0, s[60:61]
	v_cndmask_b32_e64 v108, v108, 0, s[62:63]
	v_cndmask_b32_e64 v109, v109, 0, s[64:65]
	v_cndmask_b32_e64 v110, v110, 0, s[66:67]
	v_cndmask_b32_e64 v111, v111, 0, s[68:69]
	v_cvt_pk_bf16_f32 v96, v96, v97
	v_cvt_pk_bf16_f32 v97, v98, v99
	v_cvt_pk_bf16_f32 v98, v100, v101
	v_cvt_pk_bf16_f32 v99, v102, v103
	v_cvt_pk_bf16_f32 v100, v104, v105
	v_cvt_pk_bf16_f32 v101, v106, v107
	v_cvt_pk_bf16_f32 v102, v108, v109
	v_cvt_pk_bf16_f32 v103, v110, v111
	v_mfma_f32_32x32x16_bf16 v[128:143], v[202:205], v[96:99], 0
	s_waitcnt lgkmcnt(8)
	v_mfma_f32_32x32x16_bf16 v[128:143], v[206:209], v[100:103], v[128:143]
	v_cvt_pk_bf16_f32 v218, v0, v1
	v_cvt_pk_bf16_f32 v219, v2, v3
	v_cvt_pk_bf16_f32 v220, v4, v5
	v_cvt_pk_bf16_f32 v221, v6, v7
	s_waitcnt lgkmcnt(7)
	s_nop 1
	v_mfma_f32_32x32x16_bf16 v[128:143], v[218:221], v[210:213], v[128:143]
	v_cvt_pk_bf16_f32 v222, v8, v9
	v_cvt_pk_bf16_f32 v223, v10, v11
	v_cvt_pk_bf16_f32 v224, v12, v13
	v_cvt_pk_bf16_f32 v225, v14, v15
	s_waitcnt lgkmcnt(6)
	s_nop 1
	v_mfma_f32_32x32x16_bf16 v[128:143], v[222:225], v[214:217], v[128:143]
	v_cvt_pk_bf16_f32 v218, v16, v17
	v_cvt_pk_bf16_f32 v219, v18, v19
	v_cvt_pk_bf16_f32 v220, v20, v21
	v_cvt_pk_bf16_f32 v221, v22, v23
	s_waitcnt lgkmcnt(5)
	s_nop 1
	v_mfma_f32_32x32x16_bf16 v[128:143], v[218:221], v[144:147], v[128:143]
	v_cvt_pk_bf16_f32 v222, v24, v25
	v_cvt_pk_bf16_f32 v223, v26, v27
	v_cvt_pk_bf16_f32 v224, v28, v29
	v_cvt_pk_bf16_f32 v225, v30, v31
	s_waitcnt lgkmcnt(4)
	s_nop 1
	v_mfma_f32_32x32x16_bf16 v[128:143], v[222:225], v[148:151], v[128:143]
	v_cvt_pk_bf16_f32 v218, v32, v33
	v_cvt_pk_bf16_f32 v219, v34, v35
	v_cvt_pk_bf16_f32 v220, v36, v37
	v_cvt_pk_bf16_f32 v221, v38, v39
	s_waitcnt lgkmcnt(3)
	s_nop 1
	v_mfma_f32_32x32x16_bf16 v[128:143], v[218:221], v[152:155], v[128:143]
	v_cvt_pk_bf16_f32 v222, v40, v41
	v_cvt_pk_bf16_f32 v223, v42, v43
	v_cvt_pk_bf16_f32 v224, v44, v45
	v_cvt_pk_bf16_f32 v225, v46, v47
	s_waitcnt lgkmcnt(2)
	s_nop 1
	v_mfma_f32_32x32x16_bf16 v[128:143], v[222:225], v[156:159], v[128:143]
	v_cvt_pk_bf16_f32 v218, v48, v49
	v_cvt_pk_bf16_f32 v219, v50, v51
	v_cvt_pk_bf16_f32 v220, v52, v53
	v_cvt_pk_bf16_f32 v221, v54, v55
	s_waitcnt lgkmcnt(1)
	s_nop 1
	v_mfma_f32_32x32x16_bf16 v[128:143], v[218:221], v[184:187], v[128:143]
	v_cvt_pk_bf16_f32 v222, v56, v57
	v_cvt_pk_bf16_f32 v223, v58, v59
	v_cvt_pk_bf16_f32 v224, v60, v61
	v_cvt_pk_bf16_f32 v225, v62, v63
	s_waitcnt lgkmcnt(0)
	s_nop 1
	v_mfma_f32_32x32x16_bf16 v[128:143], v[222:225], v[188:191], v[128:143]
	ds_read_b128 v[64:67], v250
	ds_read_b128 v[192:195], v226 offset:17408
	ds_read_b128 v[68:71], v250 offset:32
	ds_read_b128 v[196:199], v227 offset:17408
	ds_read_b128 v[72:75], v250 offset:64
	ds_read_b128 v[202:205], v228 offset:17408
	ds_read_b128 v[76:79], v250 offset:96
	ds_read_b128 v[206:209], v229 offset:17408
	ds_read_b128 v[80:83], v250 offset:128
	ds_read_b128 v[210:213], v230 offset:17408
	ds_read_b128 v[84:87], v250 offset:160
	ds_read_b128 v[214:217], v231 offset:17408
	s_waitcnt lgkmcnt(11)
	v_cvt_pk_bf16_f32 v218, v128, v129
	v_cvt_pk_bf16_f32 v219, v130, v131
	v_cvt_pk_bf16_f32 v220, v132, v133
	v_cvt_pk_bf16_f32 v221, v134, v135
	v_cvt_pk_bf16_f32 v222, v136, v137
	v_cvt_pk_bf16_f32 v223, v138, v139
	v_cvt_pk_bf16_f32 v224, v140, v141
	v_cvt_pk_bf16_f32 v225, v142, v143
	ds_write2_b64 v168, v[218:219], v[220:221] offset1:2
	ds_write2_b64 v168, v[222:223], v[224:225] offset0:4 offset1:6
	ds_read_b128 v[218:221], v169
	ds_read_b128 v[222:225], v170
	v_add_u32_e32 v183, s71, v171
	v_add_u32_e32 v201, s72, v171
	s_waitcnt lgkmcnt(0)
	global_store_dwordx4 v183, v[218:221], s[14:15]
	global_store_dwordx4 v201, v[222:225], s[14:15]
	ds_read_b128 v[88:91], v250 offset:192
	ds_read_b128 v[144:147], v232 offset:17408
	ds_read_b128 v[92:95], v250 offset:224
	ds_read_b128 v[148:151], v233 offset:17408
	ds_read_b128 v[152:155], v226 offset:25600
	ds_read_b128 v[156:159], v227 offset:25600
	ds_read_b128 v[184:187], v228 offset:25600
	ds_read_b128 v[188:191], v229 offset:25600
	v_mfma_f32_32x32x16_bf16 v[96:111], v[192:195], v[64:67], 0
	ds_read_b128 v[192:195], v230 offset:25600
	v_mfma_f32_32x32x16_bf16 v[96:111], v[196:199], v[68:71], v[96:111]
	ds_read_b128 v[196:199], v231 offset:25600
	v_mfma_f32_32x32x16_bf16 v[96:111], v[202:205], v[72:75], v[96:111]
	ds_read_b128 v[202:205], v232 offset:25600
	v_mfma_f32_32x32x16_bf16 v[96:111], v[206:209], v[76:79], v[96:111]
	ds_read_b128 v[206:209], v233 offset:25600
	v_mfma_f32_32x32x16_bf16 v[96:111], v[210:213], v[80:83], v[96:111]
	v_mfma_f32_32x32x16_bf16 v[96:111], v[214:217], v[84:87], v[96:111]
	s_waitcnt lgkmcnt(10)
	v_mfma_f32_32x32x16_bf16 v[96:111], v[144:147], v[88:91], v[96:111]
	ds_read_b64_tr_b16 v[210:211], v244 offset:0
	ds_read_b64_tr_b16 v[212:213], v245 offset:0
	s_waitcnt lgkmcnt(10)
	v_mfma_f32_32x32x16_bf16 v[96:111], v[148:151], v[92:95], v[96:111]
	ds_read_b64_tr_b16 v[214:215], v244 offset:4096
	ds_read_b64_tr_b16 v[216:217], v245 offset:4096
	s_waitcnt lgkmcnt(11)
	v_mfma_f32_32x32x16_bf16 v[112:127], v[152:155], v[64:67], 0
	s_waitcnt lgkmcnt(10)
	v_mfma_f32_32x32x16_bf16 v[112:127], v[156:159], v[68:71], v[112:127]
	ds_read_b64_tr_b16 v[144:145], v244 offset:8192
	ds_read_b64_tr_b16 v[146:147], v245 offset:8192
	s_waitcnt lgkmcnt(11)
	v_mfma_f32_32x32x16_bf16 v[112:127], v[184:187], v[72:75], v[112:127]
	s_waitcnt lgkmcnt(10)
	v_mfma_f32_32x32x16_bf16 v[112:127], v[188:191], v[76:79], v[112:127]
	ds_read_b64_tr_b16 v[148:149], v244 offset:12288
	ds_read_b64_tr_b16 v[150:151], v245 offset:12288
	s_waitcnt lgkmcnt(11)
	v_mfma_f32_32x32x16_bf16 v[112:127], v[192:195], v[80:83], v[112:127]
	ds_read2_b64 v[152:155], v254 offset0:0 offset1:2
	s_waitcnt lgkmcnt(11)
	v_mfma_f32_32x32x16_bf16 v[112:127], v[196:199], v[84:87], v[112:127]
	ds_read2_b64 v[156:159], v254 offset0:4 offset1:6
	s_waitcnt lgkmcnt(11)
	v_mfma_f32_32x32x16_bf16 v[112:127], v[202:205], v[88:91], v[112:127]
	ds_read2_b64 v[184:187], v254 offset0:8 offset1:10
	s_waitcnt lgkmcnt(11)
	v_mfma_f32_32x32x16_bf16 v[112:127], v[206:209], v[92:95], v[112:127]
	ds_read2_b64 v[188:191], v254 offset0:12 offset1:14
	s_waitcnt lgkmcnt(10)
	v_cvt_pk_bf16_f32 v96, v96, v97
	v_cvt_pk_bf16_f32 v97, v98, v99
	v_cvt_pk_bf16_f32 v98, v100, v101
	v_cvt_pk_bf16_f32 v99, v102, v103
	v_cvt_pk_bf16_f32 v100, v104, v105
	v_cvt_pk_bf16_f32 v101, v106, v107
	v_cvt_pk_bf16_f32 v102, v108, v109
	v_cvt_pk_bf16_f32 v103, v110, v111
	s_nop 1
	v_cndmask_b32_e64 v112, v112, 0, s[38:39]
	v_cndmask_b32_e64 v113, v113, 0, s[40:41]
	v_cndmask_b32_e64 v114, v114, 0, s[42:43]
	v_cndmask_b32_e64 v115, v115, 0, s[44:45]
	v_cndmask_b32_e64 v116, v116, 0, s[46:47]
	v_cndmask_b32_e64 v117, v117, 0, s[48:49]
	v_cndmask_b32_e64 v118, v118, 0, s[50:51]
	v_cndmask_b32_e64 v119, v119, 0, s[52:53]
	v_cndmask_b32_e64 v120, v120, 0, s[54:55]
	v_cndmask_b32_e64 v121, v121, 0, s[56:57]
	v_cndmask_b32_e64 v122, v122, 0, s[58:59]
	v_cndmask_b32_e64 v123, v123, 0, s[60:61]
	v_cndmask_b32_e64 v124, v124, 0, s[62:63]
	v_cndmask_b32_e64 v125, v125, 0, s[64:65]
	v_cndmask_b32_e64 v126, v126, 0, s[66:67]
	v_cndmask_b32_e64 v127, v127, 0, s[68:69]
	v_cvt_pk_bf16_f32 v112, v112, v113
	v_cvt_pk_bf16_f32 v113, v114, v115
	v_cvt_pk_bf16_f32 v114, v116, v117
	v_cvt_pk_bf16_f32 v115, v118, v119
	v_cvt_pk_bf16_f32 v116, v120, v121
	v_cvt_pk_bf16_f32 v117, v122, v123
	v_cvt_pk_bf16_f32 v118, v124, v125
	v_cvt_pk_bf16_f32 v119, v126, v127
	ds_read2_b64 v[192:195], v254 offset0:16 offset1:18
	ds_read2_b64 v[196:199], v254 offset0:20 offset1:22
	v_mfma_f32_32x32x16_bf16 v[128:143], v[210:213], v[96:99], 0
	s_waitcnt lgkmcnt(10)
	v_mfma_f32_32x32x16_bf16 v[128:143], v[214:217], v[100:103], v[128:143]
	ds_read2_b64 v[202:205], v254 offset0:24 offset1:26
	ds_read2_b64 v[206:209], v254 offset0:28 offset1:30
	s_waitcnt lgkmcnt(10)
	v_mfma_f32_32x32x16_bf16 v[128:143], v[144:147], v[112:115], v[128:143]
	ds_read_b64_tr_b16 v[210:211], v242 offset:0
	ds_read_b64_tr_b16 v[212:213], v243 offset:0
	s_waitcnt lgkmcnt(10)
	v_mfma_f32_32x32x16_bf16 v[128:143], v[148:151], v[116:119], v[128:143]
	v_cvt_pk_bf16_f32 v218, v0, v1
	v_cvt_pk_bf16_f32 v219, v2, v3
	v_cvt_pk_bf16_f32 v220, v4, v5
	v_cvt_pk_bf16_f32 v221, v6, v7
	ds_read_b64_tr_b16 v[214:215], v234 offset:17408
	ds_read_b64_tr_b16 v[216:217], v235 offset:17408
	s_waitcnt lgkmcnt(11)
	s_nop 1
	v_mfma_f32_32x32x16_bf16 v[128:143], v[218:221], v[152:155], v[128:143]
	v_cvt_pk_bf16_f32 v222, v8, v9
	v_cvt_pk_bf16_f32 v223, v10, v11
	v_cvt_pk_bf16_f32 v224, v12, v13
	v_cvt_pk_bf16_f32 v225, v14, v15
	s_waitcnt lgkmcnt(10)
	s_nop 1
	v_mfma_f32_32x32x16_bf16 v[128:143], v[222:225], v[156:159], v[128:143]
	v_cvt_pk_bf16_f32 v218, v16, v17
	v_cvt_pk_bf16_f32 v219, v18, v19
	v_cvt_pk_bf16_f32 v220, v20, v21
	v_cvt_pk_bf16_f32 v221, v22, v23
	ds_read_b64_tr_b16 v[144:145], v236 offset:17408
	ds_read_b64_tr_b16 v[146:147], v237 offset:17408
	s_waitcnt lgkmcnt(11)
	s_nop 1
	v_mfma_f32_32x32x16_bf16 v[128:143], v[218:221], v[184:187], v[128:143]
	v_cvt_pk_bf16_f32 v222, v24, v25
	v_cvt_pk_bf16_f32 v223, v26, v27
	v_cvt_pk_bf16_f32 v224, v28, v29
	v_cvt_pk_bf16_f32 v225, v30, v31
	s_waitcnt lgkmcnt(10)
	s_nop 1
	v_mfma_f32_32x32x16_bf16 v[128:143], v[222:225], v[188:191], v[128:143]
	v_cvt_pk_bf16_f32 v218, v32, v33
	v_cvt_pk_bf16_f32 v219, v34, v35
	v_cvt_pk_bf16_f32 v220, v36, v37
	v_cvt_pk_bf16_f32 v221, v38, v39
	ds_read_b64_tr_b16 v[148:149], v238 offset:17408
	ds_read_b64_tr_b16 v[150:151], v239 offset:17408
	s_waitcnt lgkmcnt(11)
	s_nop 1
	v_mfma_f32_32x32x16_bf16 v[128:143], v[218:221], v[192:195], v[128:143]
	v_cvt_pk_bf16_f32 v222, v40, v41
	v_cvt_pk_bf16_f32 v223, v42, v43
	v_cvt_pk_bf16_f32 v224, v44, v45
	v_cvt_pk_bf16_f32 v225, v46, v47
	s_waitcnt lgkmcnt(10)
	s_nop 1
	v_mfma_f32_32x32x16_bf16 v[128:143], v[222:225], v[196:199], v[128:143]
	v_cvt_pk_bf16_f32 v218, v48, v49
	v_cvt_pk_bf16_f32 v219, v50, v51
	v_cvt_pk_bf16_f32 v220, v52, v53
	v_cvt_pk_bf16_f32 v221, v54, v55
	ds_read_b64_tr_b16 v[152:153], v240 offset:17408
	ds_read_b64_tr_b16 v[154:155], v241 offset:17408
	s_waitcnt lgkmcnt(11)
	s_nop 1
	v_mfma_f32_32x32x16_bf16 v[128:143], v[218:221], v[202:205], v[128:143]
	v_cvt_pk_bf16_f32 v222, v56, v57
	v_cvt_pk_bf16_f32 v223, v58, v59
	v_cvt_pk_bf16_f32 v224, v60, v61
	v_cvt_pk_bf16_f32 v225, v62, v63
	s_waitcnt lgkmcnt(10)
	s_nop 1
	v_mfma_f32_32x32x16_bf16 v[128:143], v[222:225], v[206:209], v[128:143]
	ds_read_b64_tr_b16 v[156:157], v242 offset:4096
	ds_read_b64_tr_b16 v[158:159], v243 offset:4096
	s_waitcnt lgkmcnt(10)
	s_nop 8
	v_cvt_pk_bf16_f32 v218, v128, v129
	v_cvt_pk_bf16_f32 v219, v130, v131
	v_cvt_pk_bf16_f32 v220, v132, v133
	v_cvt_pk_bf16_f32 v221, v134, v135
	v_cvt_pk_bf16_f32 v222, v136, v137
	v_cvt_pk_bf16_f32 v223, v138, v139
	v_cvt_pk_bf16_f32 v224, v140, v141
	v_cvt_pk_bf16_f32 v225, v142, v143
	ds_write2_b64 v168, v[218:219], v[220:221] offset1:2
	ds_write2_b64 v168, v[222:223], v[224:225] offset0:4 offset1:6
	ds_read_b128 v[218:221], v169
	ds_read_b128 v[222:225], v170
	v_add_u32_e32 v183, s73, v171
	v_add_u32_e32 v201, s75, v171
	s_waitcnt lgkmcnt(0)
	global_store_dwordx4 v183, v[218:221], s[14:15]
	global_store_dwordx4 v201, v[222:225], s[14:15]
	ds_read_b64_tr_b16 v[184:185], v234 offset:21504
	ds_read_b64_tr_b16 v[186:187], v235 offset:21504
	ds_read_b64_tr_b16 v[188:189], v236 offset:21504
	ds_read_b64_tr_b16 v[190:191], v237 offset:21504
	ds_read_b64_tr_b16 v[192:193], v238 offset:21504
	ds_read_b64_tr_b16 v[194:195], v239 offset:21504
	ds_read_b64_tr_b16 v[196:197], v240 offset:21504
	ds_read_b64_tr_b16 v[198:199], v241 offset:21504
	ds_read_b64_tr_b16 v[202:203], v242 offset:8192
	ds_read_b64_tr_b16 v[204:205], v243 offset:8192
	ds_read_b64_tr_b16 v[206:207], v234 offset:25600
	ds_read_b64_tr_b16 v[208:209], v235 offset:25600
	v_mfma_f32_32x32x16_bf16 v[0:15], v[214:217], v[210:213], v[0:15]
	v_mfma_f32_32x32x16_bf16 v[16:31], v[144:147], v[210:213], v[16:31]
	v_mfma_f32_32x32x16_bf16 v[32:47], v[148:151], v[210:213], v[32:47]
	v_mfma_f32_32x32x16_bf16 v[48:63], v[152:155], v[210:213], v[48:63]
	s_waitcnt lgkmcnt(10)
	v_mfma_f32_32x32x16_bf16 v[0:15], v[184:187], v[156:159], v[0:15]
	ds_read_b64_tr_b16 v[214:215], v236 offset:25600
	ds_read_b64_tr_b16 v[216:217], v237 offset:25600
	s_waitcnt lgkmcnt(10)
	v_mfma_f32_32x32x16_bf16 v[16:31], v[188:191], v[156:159], v[16:31]
	ds_read_b64_tr_b16 v[144:145], v238 offset:25600
	ds_read_b64_tr_b16 v[146:147], v239 offset:25600
	s_waitcnt lgkmcnt(10)
	v_mfma_f32_32x32x16_bf16 v[32:47], v[192:195], v[156:159], v[32:47]
	ds_read_b64_tr_b16 v[148:149], v240 offset:25600
	ds_read_b64_tr_b16 v[150:151], v241 offset:25600
	s_waitcnt lgkmcnt(10)
	v_mfma_f32_32x32x16_bf16 v[48:63], v[196:199], v[156:159], v[48:63]
	ds_read_b64_tr_b16 v[152:153], v242 offset:12288
	ds_read_b64_tr_b16 v[154:155], v243 offset:12288
	s_waitcnt lgkmcnt(8)
	v_mfma_f32_32x32x16_bf16 v[0:15], v[206:209], v[202:205], v[0:15]
	ds_read_b64_tr_b16 v[210:211], v234 offset:29696
	ds_read_b64_tr_b16 v[212:213], v235 offset:29696
	ds_read_b64_tr_b16 v[184:185], v236 offset:29696
	ds_read_b64_tr_b16 v[186:187], v237 offset:29696
	s_waitcnt lgkmcnt(10)
	v_mfma_f32_32x32x16_bf16 v[16:31], v[214:217], v[202:205], v[16:31]
	ds_read_b64_tr_b16 v[188:189], v238 offset:29696
	ds_read_b64_tr_b16 v[190:191], v239 offset:29696
	s_waitcnt lgkmcnt(10)
	v_mfma_f32_32x32x16_bf16 v[32:47], v[144:147], v[202:205], v[32:47]
	ds_read_b64_tr_b16 v[192:193], v240 offset:29696
	ds_read_b64_tr_b16 v[194:195], v241 offset:29696
	s_waitcnt lgkmcnt(10)
	v_mfma_f32_32x32x16_bf16 v[48:63], v[148:151], v[202:205], v[48:63]
	ds_read_b128 v[196:199], v255 offset:512
	ds_read_b128 v[156:159], v255 offset:544
	s_waitcnt lgkmcnt(8)
	v_mfma_f32_32x32x16_bf16 v[0:15], v[210:213], v[152:155], v[0:15]
	ds_read_b128 v[206:209], v255 offset:576
	ds_read_b128 v[214:217], v255 offset:608
	ds_read_b128 v[144:147], v255 offset:640
	ds_read_b128 v[148:151], v255 offset:672
	s_waitcnt lgkmcnt(10)
	v_mfma_f32_32x32x16_bf16 v[16:31], v[184:187], v[152:155], v[16:31]
	ds_read_b128 v[202:205], v255 offset:704
	ds_read_b128 v[210:213], v255 offset:736
	s_waitcnt lgkmcnt(10)
	v_mfma_f32_32x32x16_bf16 v[32:47], v[188:191], v[152:155], v[32:47]
	ds_read_b128 v[184:187], v255 offset:768
	ds_read_b128 v[188:191], v255 offset:800
	s_waitcnt lgkmcnt(10)
	v_mfma_f32_32x32x16_bf16 v[48:63], v[192:195], v[152:155], v[48:63]
	ds_read_b128 v[192:195], v255 offset:832
	ds_read_b128 v[152:155], v255 offset:864
	s_waitcnt lgkmcnt(11)
	v_pk_mul_f32 v[0:1], v[0:1], v[196:197]
	v_pk_mul_f32 v[2:3], v[2:3], v[198:199]
	ds_read_b128 v[196:199], v255 offset:896
	s_waitcnt lgkmcnt(11)
	v_pk_mul_f32 v[4:5], v[4:5], v[156:157]
	v_pk_mul_f32 v[6:7], v[6:7], v[158:159]
	ds_read_b128 v[156:159], v255 offset:928
	s_waitcnt lgkmcnt(11)
	v_pk_mul_f32 v[8:9], v[8:9], v[206:207]
	v_pk_mul_f32 v[10:11], v[10:11], v[208:209]
	ds_read_b128 v[206:209], v255 offset:960
	s_waitcnt lgkmcnt(11)
	v_pk_mul_f32 v[12:13], v[12:13], v[214:215]
	v_pk_mul_f32 v[14:15], v[14:15], v[216:217]
	ds_read_b128 v[214:217], v255 offset:992
	s_waitcnt lgkmcnt(11)
	v_pk_mul_f32 v[16:17], v[16:17], v[144:145]
	v_pk_mul_f32 v[18:19], v[18:19], v[146:147]
	s_waitcnt lgkmcnt(10)
	v_pk_mul_f32 v[20:21], v[20:21], v[148:149]
	v_pk_mul_f32 v[22:23], v[22:23], v[150:151]
	s_waitcnt lgkmcnt(9)
	v_pk_mul_f32 v[24:25], v[24:25], v[202:203]
	v_pk_mul_f32 v[26:27], v[26:27], v[204:205]
	s_waitcnt lgkmcnt(8)
	v_pk_mul_f32 v[28:29], v[28:29], v[210:211]
	v_pk_mul_f32 v[30:31], v[30:31], v[212:213]
	s_waitcnt lgkmcnt(7)
	v_pk_mul_f32 v[32:33], v[32:33], v[184:185]
	v_pk_mul_f32 v[34:35], v[34:35], v[186:187]
	s_waitcnt lgkmcnt(6)
	v_pk_mul_f32 v[36:37], v[36:37], v[188:189]
	v_pk_mul_f32 v[38:39], v[38:39], v[190:191]
	s_waitcnt lgkmcnt(5)
	v_pk_mul_f32 v[40:41], v[40:41], v[192:193]
	v_pk_mul_f32 v[42:43], v[42:43], v[194:195]
	s_waitcnt lgkmcnt(4)
	v_pk_mul_f32 v[44:45], v[44:45], v[152:153]
	v_pk_mul_f32 v[46:47], v[46:47], v[154:155]
	s_waitcnt lgkmcnt(3)
	v_pk_mul_f32 v[48:49], v[48:49], v[196:197]
	v_pk_mul_f32 v[50:51], v[50:51], v[198:199]
	s_waitcnt lgkmcnt(2)
	v_pk_mul_f32 v[52:53], v[52:53], v[156:157]
	v_pk_mul_f32 v[54:55], v[54:55], v[158:159]
	s_waitcnt lgkmcnt(1)
	v_pk_mul_f32 v[56:57], v[56:57], v[206:207]
	v_pk_mul_f32 v[58:59], v[58:59], v[208:209]
	s_waitcnt lgkmcnt(0)
	v_pk_mul_f32 v[60:61], v[60:61], v[214:215]
	v_pk_mul_f32 v[62:63], v[62:63], v[216:217]
	v_add_u32_e32 v171, s33, v171
	s_mov_b32 s77, s76
	s_add_u32 s76, s76, 0x4000
	s_cmp_eq_u32 s76, 0x10400
	s_cselect_b32 s76, 0x24000, s76
	s_cmp_eq_u32 s76, 0x28000
	s_cselect_b32 s76, 0x8400, s76
	s_sub_u32 s77, s76, s77
	v_add_u32_e32 v244, s77, v244
	v_add_u32_e32 v245, s77, v245
	v_add_u32_e32 v242, s77, v242
	v_add_u32_e32 v243, s77, v243
	s_barrier
	s_add_u32 s70, s70, 1
	s_cmp_lt_u32 s70, 32
	s_cbranch_scc1 .Lh2_mfma_loop
	s_branch .Lh2_done
.Lh2_done:
	s_barrier
	s_branch .LBB0_445
	s_nop 0
	s_nop 0
	s_nop 0
	s_nop 0
	s_nop 0
	s_nop 0
	s_nop 0
	s_nop 0
.LBB0_445:
	v_readlane_b32 s70, v246, 54
	v_readlane_b32 s50, v246, 48
	v_readlane_b32 s68, v246, 58
	v_readlane_b32 s73, v246, 53
	v_readlane_b32 s71, v246, 55
	v_readlane_b32 s72, v246, 56
	v_readlane_b32 s54, v246, 57
	v_readlane_b32 s51, v246, 49
	v_readlane_b32 s69, v246, 59
	v_readlane_b32 s63, v246, 52

	.amdhsa_kernel _Z4mega6Params
		.amdhsa_group_segment_fixed_size 16384
		.amdhsa_private_segment_fixed_size 0
		.amdhsa_kernarg_size 416
		.amdhsa_user_sgpr_count 2
		.amdhsa_user_sgpr_dispatch_ptr 0
		.amdhsa_user_sgpr_queue_ptr 0
		.amdhsa_user_sgpr_kernarg_segment_ptr 1
		.amdhsa_user_sgpr_dispatch_id 0
		.amdhsa_user_sgpr_kernarg_preload_length 0
		.amdhsa_user_sgpr_kernarg_preload_offset 0
		.amdhsa_user_sgpr_private_segment_size 0
		.amdhsa_uses_dynamic_stack 0
		.amdhsa_enable_private_segment 0
		.amdhsa_system_sgpr_workgroup_id_x 1
		.amdhsa_system_sgpr_workgroup_id_y 0
		.amdhsa_system_sgpr_workgroup_id_z 0
		.amdhsa_system_sgpr_workgroup_info 0
		.amdhsa_system_vgpr_workitem_id 2
		.amdhsa_next_free_vgpr 256
		.amdhsa_next_free_sgpr 98
		.amdhsa_accum_offset 256
		.amdhsa_reserve_vcc 1
		.amdhsa_float_round_mode_32 0
		.amdhsa_float_round_mode_16_64 0
		.amdhsa_float_denorm_mode_32 3
		.amdhsa_float_denorm_mode_16_64 3
		.amdhsa_dx10_clamp 1
		.amdhsa_ieee_mode 1
		.amdhsa_fp16_overflow 0
		.amdhsa_tg_split 0
		.amdhsa_exception_fp_ieee_invalid_op 0
		.amdhsa_exception_fp_denorm_src 0
		.amdhsa_exception_fp_ieee_div_zero 0
		.amdhsa_exception_fp_ieee_overflow 0
		.amdhsa_exception_fp_ieee_underflow 0
		.amdhsa_exception_fp_ieee_inexact 0
		.amdhsa_exception_int_div_zero 0
	.end_amdhsa_kernel

amdhsa.kernels:
  - .agpr_count:     0
    .args:
      - .offset:         0
        .size:           160
        .value_kind:     by_value
      - .offset:         160
        .size:           4
        .value_kind:     hidden_block_count_x
      - .offset:         164
        .size:           4
        .value_kind:     hidden_block_count_y
      - .offset:         168
        .size:           4
        .value_kind:     hidden_block_count_z
      - .offset:         172
        .size:           2
        .value_kind:     hidden_group_size_x
      - .offset:         174
        .size:           2
        .value_kind:     hidden_group_size_y
      - .offset:         176
        .size:           2
        .value_kind:     hidden_group_size_z
      - .offset:         178
        .size:           2
        .value_kind:     hidden_remainder_x
      - .offset:         180
        .size:           2
        .value_kind:     hidden_remainder_y
      - .offset:         182
        .size:           2
        .value_kind:     hidden_remainder_z
      - .offset:         200
        .size:           8
        .value_kind:     hidden_global_offset_x
      - .offset:         208
        .size:           8
        .value_kind:     hidden_global_offset_y
      - .offset:         216
        .size:           8
        .value_kind:     hidden_global_offset_z
      - .offset:         224
        .size:           2
        .value_kind:     hidden_grid_dims
      - .offset:         248
        .size:           8
        .value_kind:     hidden_multigrid_sync_arg
      - .offset:         280
        .size:           4
        .value_kind:     hidden_dynamic_lds_size
    .group_segment_fixed_size: 16384
    .kernarg_segment_align: 8
    .kernarg_segment_size: 416
    .language:       OpenCL C
    .language_version:
      - 2
      - 0
    .max_flat_workgroup_size: 512
    .name:           _Z4mega6Params
    .private_segment_fixed_size: 0
    .sgpr_count:     104
    .sgpr_spill_count: 62
    .symbol:         _Z4mega6Params.kd
    .uniform_work_group_size: 1
    .uses_dynamic_stack: false
    .vgpr_count:     256
    .vgpr_spill_count: 0
    .wavefront_size: 64
